# gated-branch epilogues: 12-deep prefetch of gate/merged loads with counted waits (test vs v6)
# baseline (speedup 1.0000x reference)
; __device__ __forceinline__ u32x4 pack8(const f32x4 a, const f32x4 b) { u32x4 w; w.x = cvt_pk_bf16(a[0], a[1]); w.y = cvt_pk_bf16(a[2], a[3]); w.z = cvt_pk_bf16(b[0], b[1]); w.w = cvt_pk_bf16(b[2], b[3]); return w; }
; #define G opaque_s(G0)
;     __device__ __forceinline__ void operator()(const f32x4 (&acc)[2][2][4][2], const Unit& u, int wr, int wc, int fr, int fq) const {
;         const int row0 = u.pm * BM + wr * 64 + fr, col0 = u.pn * BM + wc * 32 + 8 * fq;
; #pragma unroll
;         for (int ai = 0; ai < 2; ++ai)
; #pragma unroll
;             for (int m = 0; m < 4; ++m) { if ((m & 1) == 0) asm volatile("" ::: "memory"); const int row = row0 + ai * HALF + m * 16;
; #pragma unroll
;                 for (int bj = 0; bj < 2; ++bj) { const size_t off = (size_t)row * 1024 + col0 + bj * HALF;
;                     f32x4 g0, g1; unpack8(*(const u32x4*)(G + off), g0, g1);
;                     f32x4 o0 = acc[ai][bj][m][0] * g0, o1 = acc[ai][bj][m][1] * g1;
;                     if (!first) { f32x4 p0, p1; unpack8(*(const u32x4*)(Mg + off), p0, p1); o0 = o0 + p0; o1 = o1 + p1; }
;                     *(u32x4*)(Mg + off) = pack8(o0, o1); } }
.LBB0_1462:
	v_lshl_add_u32 v140, s24, 8, v144
	v_lshl_or_b32 v138, s25, 8, v146
	v_ashrrev_i32_e32 v141, 31, v140
	v_ashrrev_i32_e32 v139, 31, v138
	v_lshlrev_b64 v[136:137], 10, v[140:141]
	v_lshl_add_u64 v[136:137], v[136:137], 0, v[138:139]
	v_lshlrev_b64 v[136:137], 1, v[136:137]
	v_lshl_add_u64 v[148:149], s[10:11], 0, v[136:137]
	s_mov_b64 s[60:61], s[10:11]
	global_load_dwordx4 v[166:169], v136, s[60:61]
	global_load_dwordx4 v[170:173], v136, s[60:61] offset:256
	s_add_u32 s60, s10, 0x8000
	s_addc_u32 s61, s11, 0
	global_load_dwordx4 v[174:177], v136, s[60:61]
	global_load_dwordx4 v[178:181], v136, s[60:61] offset:256
	s_add_u32 s60, s10, 0x10000
	s_addc_u32 s61, s11, 0
	global_load_dwordx4 v[182:185], v136, s[60:61]
	global_load_dwordx4 v[186:189], v136, s[60:61] offset:256
	s_add_u32 s60, s10, 0x18000
	s_addc_u32 s61, s11, 0
	global_load_dwordx4 v[190:193], v136, s[60:61]
	global_load_dwordx4 v[194:197], v136, s[60:61] offset:256
	s_add_u32 s60, s10, 0x40000
	s_addc_u32 s61, s11, 0
	global_load_dwordx4 v[198:201], v136, s[60:61]
	global_load_dwordx4 v[202:205], v136, s[60:61] offset:256
	s_add_u32 s60, s10, 0x48000
	s_addc_u32 s61, s11, 0
	global_load_dwordx4 v[206:209], v136, s[60:61]
	global_load_dwordx4 v[210:213], v136, s[60:61] offset:256
	s_mov_b64 s[0:1], 0x40100
	s_and_b64 vcc, exec, s[4:5]
	s_waitcnt vmcnt(11)
	v_mov_b64_e32 v[148:149], v[166:167]
	v_mov_b64_e32 v[150:151], v[168:169]
	v_lshlrev_b32_e32 v152, 16, v148
	v_and_b32_e32 v153, 0xffff0000, v148
	v_lshlrev_b32_e32 v148, 16, v149
	v_and_b32_e32 v149, 0xffff0000, v149
	v_lshlrev_b32_e32 v154, 16, v150
	v_and_b32_e32 v155, 0xffff0000, v150
	v_lshlrev_b32_e32 v150, 16, v151
	v_and_b32_e32 v151, 0xffff0000, v151
	v_pk_mul_f32 v[128:129], v[128:129], v[148:149]
	v_pk_mul_f32 v[126:127], v[126:127], v[152:153]
	v_pk_mul_f32 v[148:149], v[124:125], v[150:151]
	v_pk_mul_f32 v[124:125], v[122:123], v[154:155]
	v_cvt_pk_bf16_f32 v122, v126, v127
	v_cvt_pk_bf16_f32 v123, v128, v129
	v_cvt_pk_bf16_f32 v124, v124, v125
	v_cvt_pk_bf16_f32 v125, v148, v149
	v_lshl_add_u64 v[126:127], s[16:17], 0, v[136:137]
	global_store_dwordx4 v[126:127], v[122:125], off
	v_or_b32_e32 v126, 0x100, v136
	v_mov_b32_e32 v127, v137
	v_lshl_add_u64 v[122:123], s[10:11], 0, v[126:127]
	s_waitcnt vmcnt(11)
	v_mov_b64_e32 v[122:123], v[170:171]
	v_mov_b64_e32 v[124:125], v[172:173]
	s_add_u32 s60, s10, 0x50000
	s_addc_u32 s61, s11, 0
	global_load_dwordx4 v[166:169], v136, s[60:61]
	global_load_dwordx4 v[170:173], v136, s[60:61] offset:256
	v_lshlrev_b32_e32 v128, 16, v122
	v_and_b32_e32 v129, 0xffff0000, v122
	v_lshlrev_b32_e32 v122, 16, v123
	v_and_b32_e32 v123, 0xffff0000, v123
	v_lshlrev_b32_e32 v148, 16, v124
	v_and_b32_e32 v149, 0xffff0000, v124
	v_lshlrev_b32_e32 v124, 16, v125
	v_and_b32_e32 v125, 0xffff0000, v125
	v_pk_mul_f32 v[120:121], v[120:121], v[122:123]
	v_pk_mul_f32 v[118:119], v[118:119], v[128:129]
	v_pk_mul_f32 v[122:123], v[116:117], v[124:125]
	v_pk_mul_f32 v[116:117], v[114:115], v[148:149]
	v_cvt_pk_bf16_f32 v114, v118, v119
	v_cvt_pk_bf16_f32 v115, v120, v121
	v_cvt_pk_bf16_f32 v116, v116, v117
	v_cvt_pk_bf16_f32 v117, v122, v123
	v_lshl_add_u64 v[118:119], s[16:17], 0, v[126:127]
	global_store_dwordx4 v[118:119], v[114:117], off
	s_nop 1
	v_or_b32_e32 v114, 16, v140
	v_ashrrev_i32_e32 v115, 31, v114
	v_lshlrev_b64 v[114:115], 10, v[114:115]
	v_lshl_add_u64 v[114:115], v[114:115], 0, v[138:139]
	v_lshlrev_b64 v[114:115], 1, v[114:115]
	v_lshl_add_u64 v[116:117], s[10:11], 0, v[114:115]
	s_waitcnt vmcnt(13)
	v_mov_b64_e32 v[116:117], v[174:175]
	v_mov_b64_e32 v[118:119], v[176:177]
	v_lshlrev_b32_e32 v120, 16, v116
	v_and_b32_e32 v121, 0xffff0000, v116
	v_lshlrev_b32_e32 v116, 16, v117
	v_and_b32_e32 v117, 0xffff0000, v117
	v_lshlrev_b32_e32 v122, 16, v118
	v_and_b32_e32 v123, 0xffff0000, v118
	v_lshlrev_b32_e32 v118, 16, v119
	v_and_b32_e32 v119, 0xffff0000, v119
	v_pk_mul_f32 v[110:111], v[110:111], v[116:117]
	v_pk_mul_f32 v[108:109], v[108:109], v[120:121]
	v_pk_mul_f32 v[116:117], v[106:107], v[118:119]
	v_pk_mul_f32 v[106:107], v[104:105], v[122:123]
	v_cvt_pk_bf16_f32 v104, v108, v109
	v_cvt_pk_bf16_f32 v105, v110, v111
	v_cvt_pk_bf16_f32 v106, v106, v107
	v_cvt_pk_bf16_f32 v107, v116, v117
	v_lshl_add_u64 v[108:109], s[16:17], 0, v[114:115]
	v_or_b32_e32 v114, 0x100, v114
	global_store_dwordx4 v[108:109], v[104:107], off
	s_nop 1
	v_lshl_add_u64 v[104:105], s[10:11], 0, v[114:115]
	s_waitcnt vmcnt(13)
	v_mov_b64_e32 v[104:105], v[178:179]
	v_mov_b64_e32 v[106:107], v[180:181]
	s_add_u32 s60, s10, 0x58000
	s_addc_u32 s61, s11, 0
	global_load_dwordx4 v[174:177], v136, s[60:61]
	global_load_dwordx4 v[178:181], v136, s[60:61] offset:256
	v_lshlrev_b32_e32 v108, 16, v104
	v_and_b32_e32 v109, 0xffff0000, v104
	v_lshlrev_b32_e32 v104, 16, v105
	v_and_b32_e32 v105, 0xffff0000, v105
	v_lshlrev_b32_e32 v110, 16, v106
	v_and_b32_e32 v111, 0xffff0000, v106
	v_lshlrev_b32_e32 v106, 16, v107
	v_and_b32_e32 v107, 0xffff0000, v107
	v_pk_mul_f32 v[102:103], v[102:103], v[104:105]
	v_pk_mul_f32 v[100:101], v[100:101], v[108:109]
	v_pk_mul_f32 v[104:105], v[98:99], v[106:107]
	v_pk_mul_f32 v[98:99], v[96:97], v[110:111]
	v_cvt_pk_bf16_f32 v96, v100, v101
	v_cvt_pk_bf16_f32 v97, v102, v103
	v_cvt_pk_bf16_f32 v98, v98, v99
	v_cvt_pk_bf16_f32 v99, v104, v105
	v_lshl_add_u64 v[100:101], s[16:17], 0, v[114:115]
	global_store_dwordx4 v[100:101], v[96:99], off
	s_nop 1
	v_or_b32_e32 v96, 32, v140
	v_ashrrev_i32_e32 v97, 31, v96
	v_lshlrev_b64 v[96:97], 10, v[96:97]
	v_lshl_add_u64 v[96:97], v[96:97], 0, v[138:139]
	v_lshlrev_b64 v[96:97], 1, v[96:97]
	v_lshl_add_u64 v[98:99], s[10:11], 0, v[96:97]
	s_waitcnt vmcnt(15)
; __device__ __forceinline__ u32x4 pack8(const f32x4 a, const f32x4 b) { u32x4 w; w.x = cvt_pk_bf16(a[0], a[1]); w.y = cvt_pk_bf16(a[2], a[3]); w.z = cvt_pk_bf16(b[0], b[1]); w.w = cvt_pk_bf16(b[2], b[3]); return w; }
; #define G opaque_s(G0)
;     __device__ __forceinline__ void operator()(const f32x4 (&acc)[2][2][4][2], const Unit& u, int wr, int wc, int fr, int fq) const {
;     ...
;             for (int m = 0; m < 4; ++m) { if ((m & 1) == 0) asm volatile("" ::: "memory"); const int row = row0 + ai * HALF + m * 16;
; #pragma unroll
;                 for (int bj = 0; bj < 2; ++bj) { const size_t off = (size_t)row * 1024 + col0 + bj * HALF;
;                     f32x4 g0, g1; unpack8(*(const u32x4*)(G + off), g0, g1);
;                     f32x4 o0 = acc[ai][bj][m][0] * g0, o1 = acc[ai][bj][m][1] * g1;
;                     if (!first) { f32x4 p0, p1; unpack8(*(const u32x4*)(Mg + off), p0, p1); o0 = o0 + p0; o1 = o1 + p1; }
;                     *(u32x4*)(Mg + off) = pack8(o0, o1); } }
	v_mov_b64_e32 v[98:99], v[182:183]
	v_mov_b64_e32 v[100:101], v[184:185]
	v_lshlrev_b32_e32 v102, 16, v98
	v_and_b32_e32 v103, 0xffff0000, v98
	v_lshlrev_b32_e32 v98, 16, v99
	v_and_b32_e32 v99, 0xffff0000, v99
	v_lshlrev_b32_e32 v104, 16, v100
	v_and_b32_e32 v105, 0xffff0000, v100
	v_lshlrev_b32_e32 v100, 16, v101
	v_and_b32_e32 v101, 0xffff0000, v101
	v_pk_mul_f32 v[94:95], v[94:95], v[98:99]
	v_pk_mul_f32 v[92:93], v[92:93], v[102:103]
	v_pk_mul_f32 v[98:99], v[90:91], v[100:101]
	v_pk_mul_f32 v[90:91], v[88:89], v[104:105]
	v_cvt_pk_bf16_f32 v88, v92, v93
	v_cvt_pk_bf16_f32 v89, v94, v95
	v_cvt_pk_bf16_f32 v90, v90, v91
	v_cvt_pk_bf16_f32 v91, v98, v99
	v_lshl_add_u64 v[92:93], s[16:17], 0, v[96:97]
	v_or_b32_e32 v96, 0x100, v96
	global_store_dwordx4 v[92:93], v[88:91], off
	s_nop 1
	v_lshl_add_u64 v[88:89], s[10:11], 0, v[96:97]
	s_waitcnt vmcnt(15)
	v_mov_b64_e32 v[88:89], v[186:187]
	v_mov_b64_e32 v[90:91], v[188:189]
	v_lshlrev_b32_e32 v92, 16, v88
	v_and_b32_e32 v93, 0xffff0000, v88
	v_lshlrev_b32_e32 v88, 16, v89
	v_and_b32_e32 v89, 0xffff0000, v89
	v_lshlrev_b32_e32 v94, 16, v90
	v_and_b32_e32 v95, 0xffff0000, v90
	v_lshlrev_b32_e32 v90, 16, v91
	v_and_b32_e32 v91, 0xffff0000, v91
	v_pk_mul_f32 v[86:87], v[86:87], v[88:89]
	v_pk_mul_f32 v[84:85], v[84:85], v[92:93]
	v_pk_mul_f32 v[88:89], v[82:83], v[90:91]
	v_pk_mul_f32 v[82:83], v[80:81], v[94:95]
	v_cvt_pk_bf16_f32 v80, v84, v85
	v_cvt_pk_bf16_f32 v81, v86, v87
	v_cvt_pk_bf16_f32 v82, v82, v83
	v_cvt_pk_bf16_f32 v83, v88, v89
	v_lshl_add_u64 v[84:85], s[16:17], 0, v[96:97]
	global_store_dwordx4 v[84:85], v[80:83], off
	s_nop 1
	v_or_b32_e32 v80, 48, v140
	v_ashrrev_i32_e32 v81, 31, v80
	v_lshlrev_b64 v[80:81], 10, v[80:81]
	v_lshl_add_u64 v[80:81], v[80:81], 0, v[138:139]
	v_lshlrev_b64 v[80:81], 1, v[80:81]
	v_lshl_add_u64 v[82:83], s[10:11], 0, v[80:81]
	s_waitcnt vmcnt(15)
	v_mov_b64_e32 v[82:83], v[190:191]
	v_mov_b64_e32 v[84:85], v[192:193]
	v_lshlrev_b32_e32 v86, 16, v82
	v_and_b32_e32 v87, 0xffff0000, v82
	v_lshlrev_b32_e32 v82, 16, v83
	v_and_b32_e32 v83, 0xffff0000, v83
	v_lshlrev_b32_e32 v88, 16, v84
	v_and_b32_e32 v89, 0xffff0000, v84
	v_lshlrev_b32_e32 v84, 16, v85
	v_and_b32_e32 v85, 0xffff0000, v85
	v_pk_mul_f32 v[78:79], v[78:79], v[82:83]
	v_pk_mul_f32 v[76:77], v[76:77], v[86:87]
	v_pk_mul_f32 v[82:83], v[74:75], v[84:85]
	v_pk_mul_f32 v[74:75], v[72:73], v[88:89]
	v_cvt_pk_bf16_f32 v72, v76, v77
	v_cvt_pk_bf16_f32 v73, v78, v79
	v_cvt_pk_bf16_f32 v74, v74, v75
	v_cvt_pk_bf16_f32 v75, v82, v83
	v_lshl_add_u64 v[76:77], s[16:17], 0, v[80:81]
	v_or_b32_e32 v80, 0x100, v80
	global_store_dwordx4 v[76:77], v[72:75], off
	s_nop 1
	v_lshl_add_u64 v[72:73], s[10:11], 0, v[80:81]
	s_waitcnt vmcnt(15)
	v_mov_b64_e32 v[72:73], v[194:195]
	v_mov_b64_e32 v[74:75], v[196:197]
	v_lshlrev_b32_e32 v76, 16, v72
	v_and_b32_e32 v77, 0xffff0000, v72
	v_lshlrev_b32_e32 v72, 16, v73
	v_and_b32_e32 v73, 0xffff0000, v73
	v_lshlrev_b32_e32 v78, 16, v74
	v_and_b32_e32 v79, 0xffff0000, v74
	v_lshlrev_b32_e32 v74, 16, v75
	v_and_b32_e32 v75, 0xffff0000, v75
	v_pk_mul_f32 v[70:71], v[70:71], v[72:73]
	v_pk_mul_f32 v[68:69], v[68:69], v[76:77]
	v_pk_mul_f32 v[72:73], v[66:67], v[74:75]
	v_pk_mul_f32 v[66:67], v[64:65], v[78:79]
	v_cvt_pk_bf16_f32 v64, v68, v69
	v_cvt_pk_bf16_f32 v65, v70, v71
	v_cvt_pk_bf16_f32 v66, v66, v67
	v_cvt_pk_bf16_f32 v67, v72, v73
	v_lshl_add_u64 v[68:69], s[16:17], 0, v[80:81]
	global_store_dwordx4 v[68:69], v[64:67], off
	v_lshl_add_u64 v[68:69], v[136:137], 0, s[90:91]
	s_nop 0
	v_lshl_add_u64 v[64:65], s[10:11], 0, v[68:69]
	s_waitcnt vmcnt(15)
	v_mov_b64_e32 v[64:65], v[198:199]
	v_mov_b64_e32 v[66:67], v[200:201]
	v_lshlrev_b32_e32 v70, 16, v64
	v_and_b32_e32 v71, 0xffff0000, v64
	v_lshlrev_b32_e32 v64, 16, v65
	v_and_b32_e32 v65, 0xffff0000, v65
	v_lshlrev_b32_e32 v72, 16, v66
	v_and_b32_e32 v73, 0xffff0000, v66
	v_lshlrev_b32_e32 v66, 16, v67
	v_and_b32_e32 v67, 0xffff0000, v67
	v_pk_mul_f32 v[62:63], v[62:63], v[64:65]
	v_pk_mul_f32 v[60:61], v[60:61], v[70:71]
	v_pk_mul_f32 v[64:65], v[58:59], v[66:67]
	v_pk_mul_f32 v[58:59], v[56:57], v[72:73]
	v_cvt_pk_bf16_f32 v56, v60, v61
	v_cvt_pk_bf16_f32 v57, v62, v63
	v_cvt_pk_bf16_f32 v58, v58, v59
	v_cvt_pk_bf16_f32 v59, v64, v65
	v_lshl_add_u64 v[60:61], s[16:17], 0, v[68:69]
	global_store_dwordx4 v[60:61], v[56:59], off
	v_lshl_add_u64 v[60:61], v[136:137], 0, s[0:1]
	s_mov_b64 s[0:1], 0x48000
	v_lshl_add_u64 v[56:57], s[10:11], 0, v[60:61]
	s_waitcnt vmcnt(15)
	v_mov_b64_e32 v[56:57], v[202:203]
	v_mov_b64_e32 v[58:59], v[204:205]
	v_lshlrev_b32_e32 v62, 16, v56
	v_and_b32_e32 v63, 0xffff0000, v56
	v_lshlrev_b32_e32 v56, 16, v57
	v_and_b32_e32 v57, 0xffff0000, v57
	v_lshlrev_b32_e32 v64, 16, v58
	v_and_b32_e32 v65, 0xffff0000, v58
	v_lshlrev_b32_e32 v58, 16, v59
	v_and_b32_e32 v59, 0xffff0000, v59
	v_pk_mul_f32 v[54:55], v[54:55], v[56:57]
	v_pk_mul_f32 v[52:53], v[52:53], v[62:63]
	v_pk_mul_f32 v[56:57], v[50:51], v[58:59]
	v_pk_mul_f32 v[50:51], v[48:49], v[64:65]
	v_cvt_pk_bf16_f32 v48, v52, v53
	v_cvt_pk_bf16_f32 v49, v54, v55
	v_cvt_pk_bf16_f32 v50, v50, v51
	v_cvt_pk_bf16_f32 v51, v56, v57
	v_lshl_add_u64 v[52:53], s[16:17], 0, v[60:61]
	global_store_dwordx4 v[52:53], v[48:51], off
	v_lshl_add_u64 v[52:53], v[136:137], 0, s[0:1]
	s_mov_b64 s[0:1], 0x48100
	v_lshl_add_u64 v[48:49], s[10:11], 0, v[52:53]
	s_waitcnt vmcnt(15)
; __device__ __forceinline__ u32x4 pack8(const f32x4 a, const f32x4 b) { u32x4 w; w.x = cvt_pk_bf16(a[0], a[1]); w.y = cvt_pk_bf16(a[2], a[3]); w.z = cvt_pk_bf16(b[0], b[1]); w.w = cvt_pk_bf16(b[2], b[3]); return w; }
; #define G opaque_s(G0)
;     __device__ __forceinline__ void operator()(const f32x4 (&acc)[2][2][4][2], const Unit& u, int wr, int wc, int fr, int fq) const {
;     ...
;             for (int m = 0; m < 4; ++m) { if ((m & 1) == 0) asm volatile("" ::: "memory"); const int row = row0 + ai * HALF + m * 16;
; #pragma unroll
;                 for (int bj = 0; bj < 2; ++bj) { const size_t off = (size_t)row * 1024 + col0 + bj * HALF;
;                     f32x4 g0, g1; unpack8(*(const u32x4*)(G + off), g0, g1);
;                     f32x4 o0 = acc[ai][bj][m][0] * g0, o1 = acc[ai][bj][m][1] * g1;
;                     if (!first) { f32x4 p0, p1; unpack8(*(const u32x4*)(Mg + off), p0, p1); o0 = o0 + p0; o1 = o1 + p1; }
;                     *(u32x4*)(Mg + off) = pack8(o0, o1); } }
	v_mov_b64_e32 v[48:49], v[206:207]
	v_mov_b64_e32 v[50:51], v[208:209]
	v_lshlrev_b32_e32 v54, 16, v48
	v_and_b32_e32 v55, 0xffff0000, v48
	v_lshlrev_b32_e32 v48, 16, v49
	v_and_b32_e32 v49, 0xffff0000, v49
	v_lshlrev_b32_e32 v56, 16, v50
	v_and_b32_e32 v57, 0xffff0000, v50
	v_lshlrev_b32_e32 v50, 16, v51
	v_and_b32_e32 v51, 0xffff0000, v51
	v_pk_mul_f32 v[46:47], v[46:47], v[48:49]
	v_pk_mul_f32 v[44:45], v[44:45], v[54:55]
	v_pk_mul_f32 v[48:49], v[42:43], v[50:51]
	v_pk_mul_f32 v[42:43], v[40:41], v[56:57]
	v_cvt_pk_bf16_f32 v40, v44, v45
	v_cvt_pk_bf16_f32 v41, v46, v47
	v_cvt_pk_bf16_f32 v42, v42, v43
	v_cvt_pk_bf16_f32 v43, v48, v49
	v_lshl_add_u64 v[44:45], s[16:17], 0, v[52:53]
	global_store_dwordx4 v[44:45], v[40:43], off
	v_lshl_add_u64 v[44:45], v[136:137], 0, s[0:1]
	s_mov_b64 s[0:1], 0x50000
	v_lshl_add_u64 v[40:41], s[10:11], 0, v[44:45]
	s_waitcnt vmcnt(15)
	v_mov_b64_e32 v[40:41], v[210:211]
	v_mov_b64_e32 v[42:43], v[212:213]
	v_lshlrev_b32_e32 v46, 16, v40
	v_and_b32_e32 v47, 0xffff0000, v40
	v_lshlrev_b32_e32 v40, 16, v41
	v_and_b32_e32 v41, 0xffff0000, v41
	v_lshlrev_b32_e32 v48, 16, v42
	v_and_b32_e32 v49, 0xffff0000, v42
	v_lshlrev_b32_e32 v42, 16, v43
	v_and_b32_e32 v43, 0xffff0000, v43
	v_pk_mul_f32 v[38:39], v[38:39], v[40:41]
	v_pk_mul_f32 v[36:37], v[36:37], v[46:47]
	v_pk_mul_f32 v[40:41], v[34:35], v[42:43]
	v_pk_mul_f32 v[34:35], v[32:33], v[48:49]
	v_cvt_pk_bf16_f32 v32, v36, v37
	v_cvt_pk_bf16_f32 v33, v38, v39
	v_cvt_pk_bf16_f32 v34, v34, v35
	v_cvt_pk_bf16_f32 v35, v40, v41
	v_lshl_add_u64 v[36:37], s[16:17], 0, v[44:45]
	global_store_dwordx4 v[36:37], v[32:35], off
	v_lshl_add_u64 v[36:37], v[136:137], 0, s[0:1]
	s_mov_b64 s[0:1], 0x50100
	v_lshl_add_u64 v[32:33], s[10:11], 0, v[36:37]
	s_waitcnt vmcnt(14)
	v_mov_b64_e32 v[32:33], v[166:167]
	v_mov_b64_e32 v[34:35], v[168:169]
	v_lshlrev_b32_e32 v38, 16, v32
	v_and_b32_e32 v39, 0xffff0000, v32
	v_lshlrev_b32_e32 v32, 16, v33
	v_and_b32_e32 v33, 0xffff0000, v33
	v_lshlrev_b32_e32 v40, 16, v34
	v_and_b32_e32 v41, 0xffff0000, v34
	v_lshlrev_b32_e32 v34, 16, v35
	v_and_b32_e32 v35, 0xffff0000, v35
	v_pk_mul_f32 v[30:31], v[30:31], v[32:33]
	v_pk_mul_f32 v[28:29], v[28:29], v[38:39]
	v_pk_mul_f32 v[32:33], v[26:27], v[34:35]
	v_pk_mul_f32 v[26:27], v[24:25], v[40:41]
	v_cvt_pk_bf16_f32 v24, v28, v29
	v_cvt_pk_bf16_f32 v25, v30, v31
	v_cvt_pk_bf16_f32 v26, v26, v27
	v_cvt_pk_bf16_f32 v27, v32, v33
	v_lshl_add_u64 v[28:29], s[16:17], 0, v[36:37]
	global_store_dwordx4 v[28:29], v[24:27], off
	v_lshl_add_u64 v[28:29], v[136:137], 0, s[0:1]
	s_mov_b64 s[0:1], 0x58100
	v_lshl_add_u64 v[24:25], s[10:11], 0, v[28:29]
	s_waitcnt vmcnt(14)
	v_mov_b64_e32 v[24:25], v[170:171]
	v_mov_b64_e32 v[26:27], v[172:173]
	v_lshlrev_b32_e32 v30, 16, v24
	v_and_b32_e32 v31, 0xffff0000, v24
	v_lshlrev_b32_e32 v24, 16, v25
	v_and_b32_e32 v25, 0xffff0000, v25
	v_lshlrev_b32_e32 v32, 16, v26
	v_and_b32_e32 v33, 0xffff0000, v26
	v_lshlrev_b32_e32 v26, 16, v27
	v_and_b32_e32 v27, 0xffff0000, v27
	v_pk_mul_f32 v[22:23], v[22:23], v[24:25]
	v_pk_mul_f32 v[20:21], v[20:21], v[30:31]
	v_pk_mul_f32 v[24:25], v[18:19], v[26:27]
	v_pk_mul_f32 v[18:19], v[16:17], v[32:33]
	v_cvt_pk_bf16_f32 v16, v20, v21
	v_cvt_pk_bf16_f32 v17, v22, v23
	v_cvt_pk_bf16_f32 v18, v18, v19
	v_cvt_pk_bf16_f32 v19, v24, v25
	v_lshl_add_u64 v[20:21], s[16:17], 0, v[28:29]
	global_store_dwordx4 v[20:21], v[16:19], off
	v_lshl_add_u64 v[20:21], v[136:137], 0, s[78:79]
	s_nop 0
	v_lshl_add_u64 v[16:17], s[10:11], 0, v[20:21]
	s_waitcnt vmcnt(12)
	v_mov_b64_e32 v[16:17], v[174:175]
	v_mov_b64_e32 v[18:19], v[176:177]
	v_lshlrev_b32_e32 v22, 16, v16
	v_and_b32_e32 v23, 0xffff0000, v16
	v_lshlrev_b32_e32 v16, 16, v17
	v_and_b32_e32 v17, 0xffff0000, v17
	v_lshlrev_b32_e32 v24, 16, v18
	v_and_b32_e32 v25, 0xffff0000, v18
	v_lshlrev_b32_e32 v18, 16, v19
	v_and_b32_e32 v19, 0xffff0000, v19
	v_pk_mul_f32 v[14:15], v[14:15], v[16:17]
	v_pk_mul_f32 v[12:13], v[12:13], v[22:23]
	v_pk_mul_f32 v[16:17], v[10:11], v[18:19]
	v_pk_mul_f32 v[10:11], v[8:9], v[24:25]
	v_cvt_pk_bf16_f32 v8, v12, v13
	v_cvt_pk_bf16_f32 v9, v14, v15
	v_cvt_pk_bf16_f32 v10, v10, v11
	v_cvt_pk_bf16_f32 v11, v16, v17
	v_lshl_add_u64 v[12:13], s[16:17], 0, v[20:21]
	global_store_dwordx4 v[12:13], v[8:11], off
	v_lshl_add_u64 v[12:13], v[136:137], 0, s[0:1]
	s_mov_b64 s[0:1], -1
	v_lshl_add_u64 v[8:9], s[10:11], 0, v[12:13]
	s_waitcnt vmcnt(12)
	v_mov_b64_e32 v[8:9], v[178:179]
	v_mov_b64_e32 v[10:11], v[180:181]
	v_lshlrev_b32_e32 v14, 16, v8
	v_and_b32_e32 v15, 0xffff0000, v8
	v_lshlrev_b32_e32 v8, 16, v9
	v_and_b32_e32 v9, 0xffff0000, v9
	v_lshlrev_b32_e32 v16, 16, v10
	v_and_b32_e32 v17, 0xffff0000, v10
	v_lshlrev_b32_e32 v10, 16, v11
	v_and_b32_e32 v11, 0xffff0000, v11
	v_pk_mul_f32 v[6:7], v[6:7], v[8:9]
	v_pk_mul_f32 v[4:5], v[4:5], v[14:15]
	v_pk_mul_f32 v[8:9], v[2:3], v[10:11]
	v_pk_mul_f32 v[2:3], v[0:1], v[16:17]
	v_cvt_pk_bf16_f32 v0, v4, v5
	v_cvt_pk_bf16_f32 v1, v6, v7
	v_cvt_pk_bf16_f32 v2, v2, v3
	v_cvt_pk_bf16_f32 v3, v8, v9
	v_lshl_add_u64 v[4:5], s[16:17], 0, v[12:13]
	global_store_dwordx4 v[4:5], v[0:3], off
	s_cbranch_vccnz .LBB0_1449
	s_andn2_b64 vcc, exec, s[8:9]
	s_cbranch_vccnz .LBB0_1448
	s_barrier
	s_branch .LBB0_1448

; __device__ __forceinline__ u32x4 pack8(const f32x4 a, const f32x4 b) { u32x4 w; w.x = cvt_pk_bf16(a[0], a[1]); w.y = cvt_pk_bf16(a[2], a[3]); w.z = cvt_pk_bf16(b[0], b[1]); w.w = cvt_pk_bf16(b[2], b[3]); return w; }
; #define G opaque_s(G0)
;     __device__ __forceinline__ void operator()(const f32x4 (&acc)[2][2][4][2], const Unit& u, int wr, int wc, int fr, int fq) const {
;     ...
;             for (int m = 0; m < 4; ++m) { if ((m & 1) == 0) asm volatile("" ::: "memory"); const int row = row0 + ai * HALF + m * 16;
; #pragma unroll
;                 for (int bj = 0; bj < 2; ++bj) { const size_t off = (size_t)row * 1024 + col0 + bj * HALF;
;                     f32x4 g0, g1; unpack8(*(const u32x4*)(G + off), g0, g1);
;                     f32x4 o0 = acc[ai][bj][m][0] * g0, o1 = acc[ai][bj][m][1] * g1;
;                     if (!first) { f32x4 p0, p1; unpack8(*(const u32x4*)(Mg + off), p0, p1); o0 = o0 + p0; o1 = o1 + p1; }
;                     *(u32x4*)(Mg + off) = pack8(o0, o1); } }
.LBB0_1512:
	v_lshl_add_u32 v140, s24, 8, v144
	v_lshl_or_b32 v138, s25, 8, v146
	v_ashrrev_i32_e32 v141, 31, v140
	v_ashrrev_i32_e32 v139, 31, v138
	v_lshlrev_b64 v[136:137], 10, v[140:141]
	v_lshl_add_u64 v[136:137], v[136:137], 0, v[138:139]
	v_lshlrev_b64 v[136:137], 1, v[136:137]
	v_lshl_add_u64 v[148:149], s[10:11], 0, v[136:137]
	s_mov_b64 s[60:61], s[10:11]
	s_mov_b64 s[62:63], s[16:17]
	global_load_dwordx4 v[166:169], v136, s[60:61]
	global_load_dwordx4 v[170:173], v136, s[62:63]
	global_load_dwordx4 v[174:177], v136, s[60:61] offset:256
	global_load_dwordx4 v[178:181], v136, s[62:63] offset:256
	s_add_u32 s60, s10, 0x8000
	s_addc_u32 s61, s11, 0
	s_add_u32 s62, s16, 0x8000
	s_addc_u32 s63, s17, 0
	global_load_dwordx4 v[182:185], v136, s[60:61]
	global_load_dwordx4 v[186:189], v136, s[62:63]
	global_load_dwordx4 v[190:193], v136, s[60:61] offset:256
	global_load_dwordx4 v[194:197], v136, s[62:63] offset:256
	s_add_u32 s60, s10, 0x10000
	s_addc_u32 s61, s11, 0
	s_add_u32 s62, s16, 0x10000
	s_addc_u32 s63, s17, 0
	global_load_dwordx4 v[198:201], v136, s[60:61]
	global_load_dwordx4 v[202:205], v136, s[62:63]
	global_load_dwordx4 v[206:209], v136, s[60:61] offset:256
	global_load_dwordx4 v[210:213], v136, s[62:63] offset:256
	v_lshl_add_u64 v[160:161], s[16:17], 0, v[136:137]
	s_mov_b64 s[0:1], 0x40100
	s_and_b64 vcc, exec, s[4:5]
	s_waitcnt vmcnt(11)
	v_mov_b64_e32 v[148:149], v[166:167]
	v_mov_b64_e32 v[150:151], v[168:169]
	v_lshlrev_b32_e32 v152, 16, v148
	v_and_b32_e32 v153, 0xffff0000, v148
	v_lshlrev_b32_e32 v154, 16, v149
	v_and_b32_e32 v155, 0xffff0000, v149
	v_lshlrev_b32_e32 v156, 16, v150
	v_and_b32_e32 v157, 0xffff0000, v150
	v_lshlrev_b32_e32 v158, 16, v151
	v_and_b32_e32 v159, 0xffff0000, v151
	s_waitcnt vmcnt(10)
	v_mov_b64_e32 v[148:149], v[170:171]
	v_mov_b64_e32 v[150:151], v[172:173]
	v_lshlrev_b32_e32 v162, 16, v148
	v_and_b32_e32 v163, 0xffff0000, v148
	v_lshlrev_b32_e32 v148, 16, v149
	v_and_b32_e32 v149, 0xffff0000, v149
	v_lshlrev_b32_e32 v164, 16, v150
	v_and_b32_e32 v165, 0xffff0000, v150
	v_lshlrev_b32_e32 v150, 16, v151
	v_and_b32_e32 v151, 0xffff0000, v151
	v_pk_fma_f32 v[128:129], v[128:129], v[154:155], v[148:149]
	v_pk_fma_f32 v[126:127], v[126:127], v[152:153], v[162:163]
	v_pk_fma_f32 v[148:149], v[124:125], v[158:159], v[150:151]
	v_pk_fma_f32 v[124:125], v[122:123], v[156:157], v[164:165]
	v_cvt_pk_bf16_f32 v122, v126, v127
	v_cvt_pk_bf16_f32 v123, v128, v129
	v_cvt_pk_bf16_f32 v124, v124, v125
	v_cvt_pk_bf16_f32 v125, v148, v149
	v_or_b32_e32 v126, 0x100, v136
	v_mov_b32_e32 v127, v137
	global_store_dwordx4 v[160:161], v[122:125], off
	s_nop 1
	v_lshl_add_u64 v[122:123], s[10:11], 0, v[126:127]
	v_lshl_add_u64 v[126:127], s[16:17], 0, v[126:127]
	s_waitcnt vmcnt(10)
	v_mov_b64_e32 v[122:123], v[174:175]
	v_mov_b64_e32 v[124:125], v[176:177]
	v_lshlrev_b32_e32 v128, 16, v122
	v_and_b32_e32 v129, 0xffff0000, v122
	v_lshlrev_b32_e32 v148, 16, v123
	v_and_b32_e32 v149, 0xffff0000, v123
	v_lshlrev_b32_e32 v150, 16, v124
	v_and_b32_e32 v151, 0xffff0000, v124
	v_lshlrev_b32_e32 v152, 16, v125
	v_and_b32_e32 v153, 0xffff0000, v125
	s_waitcnt vmcnt(9)
	v_mov_b64_e32 v[122:123], v[178:179]
	v_mov_b64_e32 v[124:125], v[180:181]
	s_add_u32 s60, s10, 0x18000
	s_addc_u32 s61, s11, 0
	s_add_u32 s62, s16, 0x18000
	s_addc_u32 s63, s17, 0
	global_load_dwordx4 v[166:169], v136, s[60:61]
	global_load_dwordx4 v[170:173], v136, s[62:63]
	global_load_dwordx4 v[174:177], v136, s[60:61] offset:256
	global_load_dwordx4 v[178:181], v136, s[62:63] offset:256
	v_lshlrev_b32_e32 v154, 16, v122
	v_and_b32_e32 v155, 0xffff0000, v122
	v_lshlrev_b32_e32 v122, 16, v123
	v_and_b32_e32 v123, 0xffff0000, v123
	v_lshlrev_b32_e32 v156, 16, v124
	v_and_b32_e32 v157, 0xffff0000, v124
	v_lshlrev_b32_e32 v124, 16, v125
	v_and_b32_e32 v125, 0xffff0000, v125
	v_pk_fma_f32 v[120:121], v[120:121], v[148:149], v[122:123]
	v_pk_fma_f32 v[118:119], v[118:119], v[128:129], v[154:155]
	v_pk_fma_f32 v[122:123], v[116:117], v[152:153], v[124:125]
	v_pk_fma_f32 v[116:117], v[114:115], v[150:151], v[156:157]
	v_cvt_pk_bf16_f32 v114, v118, v119
	v_cvt_pk_bf16_f32 v115, v120, v121
	v_cvt_pk_bf16_f32 v116, v116, v117
	v_cvt_pk_bf16_f32 v117, v122, v123
	global_store_dwordx4 v[126:127], v[114:117], off
	s_nop 1
	v_or_b32_e32 v114, 16, v140
	v_ashrrev_i32_e32 v115, 31, v114
	v_lshlrev_b64 v[114:115], 10, v[114:115]
	v_lshl_add_u64 v[114:115], v[114:115], 0, v[138:139]
	v_lshlrev_b64 v[114:115], 1, v[114:115]
	v_lshl_add_u64 v[116:117], s[10:11], 0, v[114:115]
	v_lshl_add_u64 v[128:129], s[16:17], 0, v[114:115]
	v_or_b32_e32 v114, 0x100, v114
	s_waitcnt vmcnt(13)
	v_mov_b64_e32 v[116:117], v[182:183]
	v_mov_b64_e32 v[118:119], v[184:185]
	v_lshlrev_b32_e32 v120, 16, v116
	v_and_b32_e32 v121, 0xffff0000, v116
	v_lshlrev_b32_e32 v122, 16, v117
	v_and_b32_e32 v123, 0xffff0000, v117
	v_lshlrev_b32_e32 v124, 16, v118
	v_and_b32_e32 v125, 0xffff0000, v118
	v_lshlrev_b32_e32 v126, 16, v119
	v_and_b32_e32 v127, 0xffff0000, v119
	s_waitcnt vmcnt(12)
	v_mov_b64_e32 v[116:117], v[186:187]
	v_mov_b64_e32 v[118:119], v[188:189]
	v_lshlrev_b32_e32 v148, 16, v116
	v_and_b32_e32 v149, 0xffff0000, v116
	v_lshlrev_b32_e32 v116, 16, v117
	v_and_b32_e32 v117, 0xffff0000, v117
	v_lshlrev_b32_e32 v150, 16, v118
	v_and_b32_e32 v151, 0xffff0000, v118
	v_lshlrev_b32_e32 v118, 16, v119
	v_and_b32_e32 v119, 0xffff0000, v119
	v_pk_fma_f32 v[110:111], v[110:111], v[122:123], v[116:117]
	v_pk_fma_f32 v[108:109], v[108:109], v[120:121], v[148:149]
	v_pk_fma_f32 v[116:117], v[106:107], v[126:127], v[118:119]
	v_pk_fma_f32 v[106:107], v[104:105], v[124:125], v[150:151]
	v_cvt_pk_bf16_f32 v104, v108, v109
	v_cvt_pk_bf16_f32 v105, v110, v111
	v_cvt_pk_bf16_f32 v106, v106, v107
	v_cvt_pk_bf16_f32 v107, v116, v117
	global_store_dwordx4 v[128:129], v[104:107], off
	s_nop 1
	v_lshl_add_u64 v[104:105], s[10:11], 0, v[114:115]
	v_lshl_add_u64 v[114:115], s[16:17], 0, v[114:115]
	s_waitcnt vmcnt(12)
; __device__ __forceinline__ u32x4 pack8(const f32x4 a, const f32x4 b) { u32x4 w; w.x = cvt_pk_bf16(a[0], a[1]); w.y = cvt_pk_bf16(a[2], a[3]); w.z = cvt_pk_bf16(b[0], b[1]); w.w = cvt_pk_bf16(b[2], b[3]); return w; }
; #define G opaque_s(G0)
;     __device__ __forceinline__ void operator()(const f32x4 (&acc)[2][2][4][2], const Unit& u, int wr, int wc, int fr, int fq) const {
;         const int row0 = u.pm * BM + wr * 64 + fr, col0 = u.pn * BM + wc * 32 + 8 * fq;
; #pragma unroll
;         for (int ai = 0; ai < 2; ++ai)
; #pragma unroll
;             for (int m = 0; m < 4; ++m) { if ((m & 1) == 0) asm volatile("" ::: "memory"); const int row = row0 + ai * HALF + m * 16;
; #pragma unroll
;                 for (int bj = 0; bj < 2; ++bj) { const size_t off = (size_t)row * 1024 + col0 + bj * HALF;
;                     f32x4 g0, g1; unpack8(*(const u32x4*)(G + off), g0, g1);
;                     f32x4 o0 = acc[ai][bj][m][0] * g0, o1 = acc[ai][bj][m][1] * g1;
;                     if (!first) { f32x4 p0, p1; unpack8(*(const u32x4*)(Mg + off), p0, p1); o0 = o0 + p0; o1 = o1 + p1; }
;                     *(u32x4*)(Mg + off) = pack8(o0, o1); } }
	v_mov_b64_e32 v[104:105], v[190:191]
	v_mov_b64_e32 v[106:107], v[192:193]
	v_lshlrev_b32_e32 v108, 16, v104
	v_and_b32_e32 v109, 0xffff0000, v104
	v_lshlrev_b32_e32 v110, 16, v105
	v_and_b32_e32 v111, 0xffff0000, v105
	v_lshlrev_b32_e32 v116, 16, v106
	v_and_b32_e32 v117, 0xffff0000, v106
	v_lshlrev_b32_e32 v118, 16, v107
	v_and_b32_e32 v119, 0xffff0000, v107
	s_waitcnt vmcnt(11)
	v_mov_b64_e32 v[104:105], v[194:195]
	v_mov_b64_e32 v[106:107], v[196:197]
	s_add_u32 s60, s10, 0x40000
	s_addc_u32 s61, s11, 0
	s_add_u32 s62, s16, 0x40000
	s_addc_u32 s63, s17, 0
	global_load_dwordx4 v[182:185], v136, s[60:61]
	global_load_dwordx4 v[186:189], v136, s[62:63]
	global_load_dwordx4 v[190:193], v136, s[60:61] offset:256
	global_load_dwordx4 v[194:197], v136, s[62:63] offset:256
	v_lshlrev_b32_e32 v120, 16, v104
	v_and_b32_e32 v121, 0xffff0000, v104
	v_lshlrev_b32_e32 v104, 16, v105
	v_and_b32_e32 v105, 0xffff0000, v105
	v_lshlrev_b32_e32 v122, 16, v106
	v_and_b32_e32 v123, 0xffff0000, v106
	v_lshlrev_b32_e32 v106, 16, v107
	v_and_b32_e32 v107, 0xffff0000, v107
	v_pk_fma_f32 v[102:103], v[102:103], v[110:111], v[104:105]
	v_pk_fma_f32 v[100:101], v[100:101], v[108:109], v[120:121]
	v_pk_fma_f32 v[104:105], v[98:99], v[118:119], v[106:107]
	v_pk_fma_f32 v[98:99], v[96:97], v[116:117], v[122:123]
	v_cvt_pk_bf16_f32 v96, v100, v101
	v_cvt_pk_bf16_f32 v97, v102, v103
	v_cvt_pk_bf16_f32 v98, v98, v99
	v_cvt_pk_bf16_f32 v99, v104, v105
	global_store_dwordx4 v[114:115], v[96:99], off
	s_nop 1
	v_or_b32_e32 v96, 32, v140
	v_ashrrev_i32_e32 v97, 31, v96
	v_lshlrev_b64 v[96:97], 10, v[96:97]
	v_lshl_add_u64 v[96:97], v[96:97], 0, v[138:139]
	v_lshlrev_b64 v[96:97], 1, v[96:97]
	v_lshl_add_u64 v[98:99], s[10:11], 0, v[96:97]
	v_lshl_add_u64 v[110:111], s[16:17], 0, v[96:97]
	v_or_b32_e32 v96, 0x100, v96
	s_waitcnt vmcnt(15)
	v_mov_b64_e32 v[98:99], v[198:199]
	v_mov_b64_e32 v[100:101], v[200:201]
	v_lshlrev_b32_e32 v102, 16, v98
	v_and_b32_e32 v103, 0xffff0000, v98
	v_lshlrev_b32_e32 v104, 16, v99
	v_and_b32_e32 v105, 0xffff0000, v99
	v_lshlrev_b32_e32 v106, 16, v100
	v_and_b32_e32 v107, 0xffff0000, v100
	v_lshlrev_b32_e32 v108, 16, v101
	v_and_b32_e32 v109, 0xffff0000, v101
	s_waitcnt vmcnt(14)
	v_mov_b64_e32 v[98:99], v[202:203]
	v_mov_b64_e32 v[100:101], v[204:205]
	v_lshlrev_b32_e32 v114, 16, v98
	v_and_b32_e32 v115, 0xffff0000, v98
	v_lshlrev_b32_e32 v98, 16, v99
	v_and_b32_e32 v99, 0xffff0000, v99
	v_lshlrev_b32_e32 v116, 16, v100
	v_and_b32_e32 v117, 0xffff0000, v100
	v_lshlrev_b32_e32 v100, 16, v101
	v_and_b32_e32 v101, 0xffff0000, v101
	v_pk_fma_f32 v[94:95], v[94:95], v[104:105], v[98:99]
	v_pk_fma_f32 v[92:93], v[92:93], v[102:103], v[114:115]
	v_pk_fma_f32 v[98:99], v[90:91], v[108:109], v[100:101]
	v_pk_fma_f32 v[90:91], v[88:89], v[106:107], v[116:117]
	v_cvt_pk_bf16_f32 v88, v92, v93
	v_cvt_pk_bf16_f32 v89, v94, v95
	v_cvt_pk_bf16_f32 v90, v90, v91
	v_cvt_pk_bf16_f32 v91, v98, v99
	global_store_dwordx4 v[110:111], v[88:91], off
	s_nop 1
	v_lshl_add_u64 v[88:89], s[10:11], 0, v[96:97]
	v_lshl_add_u64 v[96:97], s[16:17], 0, v[96:97]
	s_waitcnt vmcnt(14)
	v_mov_b64_e32 v[88:89], v[206:207]
	v_mov_b64_e32 v[90:91], v[208:209]
	v_lshlrev_b32_e32 v92, 16, v88
	v_and_b32_e32 v93, 0xffff0000, v88
	v_lshlrev_b32_e32 v94, 16, v89
	v_and_b32_e32 v95, 0xffff0000, v89
	v_lshlrev_b32_e32 v98, 16, v90
	v_and_b32_e32 v99, 0xffff0000, v90
	v_lshlrev_b32_e32 v100, 16, v91
	v_and_b32_e32 v101, 0xffff0000, v91
	s_waitcnt vmcnt(13)
	v_mov_b64_e32 v[88:89], v[210:211]
	v_mov_b64_e32 v[90:91], v[212:213]
	s_add_u32 s60, s10, 0x48000
	s_addc_u32 s61, s11, 0
	s_add_u32 s62, s16, 0x48000
	s_addc_u32 s63, s17, 0
	global_load_dwordx4 v[198:201], v136, s[60:61]
	global_load_dwordx4 v[202:205], v136, s[62:63]
	global_load_dwordx4 v[206:209], v136, s[60:61] offset:256
	global_load_dwordx4 v[210:213], v136, s[62:63] offset:256
	v_lshlrev_b32_e32 v102, 16, v88
	v_and_b32_e32 v103, 0xffff0000, v88
	v_lshlrev_b32_e32 v88, 16, v89
	v_and_b32_e32 v89, 0xffff0000, v89
	v_lshlrev_b32_e32 v104, 16, v90
	v_and_b32_e32 v105, 0xffff0000, v90
	v_lshlrev_b32_e32 v90, 16, v91
	v_and_b32_e32 v91, 0xffff0000, v91
	v_pk_fma_f32 v[86:87], v[86:87], v[94:95], v[88:89]
	v_pk_fma_f32 v[84:85], v[84:85], v[92:93], v[102:103]
	v_pk_fma_f32 v[88:89], v[82:83], v[100:101], v[90:91]
	v_pk_fma_f32 v[82:83], v[80:81], v[98:99], v[104:105]
	v_cvt_pk_bf16_f32 v80, v84, v85
	v_cvt_pk_bf16_f32 v81, v86, v87
	v_cvt_pk_bf16_f32 v82, v82, v83
	v_cvt_pk_bf16_f32 v83, v88, v89
	global_store_dwordx4 v[96:97], v[80:83], off
	s_nop 1
	v_or_b32_e32 v80, 48, v140
	v_ashrrev_i32_e32 v81, 31, v80
	v_lshlrev_b64 v[80:81], 10, v[80:81]
	v_lshl_add_u64 v[80:81], v[80:81], 0, v[138:139]
	v_lshlrev_b64 v[80:81], 1, v[80:81]
	v_lshl_add_u64 v[82:83], s[10:11], 0, v[80:81]
	v_lshl_add_u64 v[94:95], s[16:17], 0, v[80:81]
	v_or_b32_e32 v80, 0x100, v80
	s_waitcnt vmcnt(16)
	v_mov_b64_e32 v[82:83], v[166:167]
	v_mov_b64_e32 v[84:85], v[168:169]
	v_lshlrev_b32_e32 v86, 16, v82
	v_and_b32_e32 v87, 0xffff0000, v82
	v_lshlrev_b32_e32 v88, 16, v83
	v_and_b32_e32 v89, 0xffff0000, v83
	v_lshlrev_b32_e32 v90, 16, v84
	v_and_b32_e32 v91, 0xffff0000, v84
	v_lshlrev_b32_e32 v92, 16, v85
	v_and_b32_e32 v93, 0xffff0000, v85
	s_waitcnt vmcnt(15)
; __device__ __forceinline__ u32x4 pack8(const f32x4 a, const f32x4 b) { u32x4 w; w.x = cvt_pk_bf16(a[0], a[1]); w.y = cvt_pk_bf16(a[2], a[3]); w.z = cvt_pk_bf16(b[0], b[1]); w.w = cvt_pk_bf16(b[2], b[3]); return w; }
; #define G opaque_s(G0)
;     __device__ __forceinline__ void operator()(const f32x4 (&acc)[2][2][4][2], const Unit& u, int wr, int wc, int fr, int fq) const {
;         const int row0 = u.pm * BM + wr * 64 + fr, col0 = u.pn * BM + wc * 32 + 8 * fq;
; #pragma unroll
;         for (int ai = 0; ai < 2; ++ai)
; #pragma unroll
;             for (int m = 0; m < 4; ++m) { if ((m & 1) == 0) asm volatile("" ::: "memory"); const int row = row0 + ai * HALF + m * 16;
; #pragma unroll
;                 for (int bj = 0; bj < 2; ++bj) { const size_t off = (size_t)row * 1024 + col0 + bj * HALF;
;                     f32x4 g0, g1; unpack8(*(const u32x4*)(G + off), g0, g1);
;                     f32x4 o0 = acc[ai][bj][m][0] * g0, o1 = acc[ai][bj][m][1] * g1;
;                     if (!first) { f32x4 p0, p1; unpack8(*(const u32x4*)(Mg + off), p0, p1); o0 = o0 + p0; o1 = o1 + p1; }
;                     *(u32x4*)(Mg + off) = pack8(o0, o1); } }
	v_mov_b64_e32 v[82:83], v[170:171]
	v_mov_b64_e32 v[84:85], v[172:173]
	v_lshlrev_b32_e32 v96, 16, v82
	v_and_b32_e32 v97, 0xffff0000, v82
	v_lshlrev_b32_e32 v82, 16, v83
	v_and_b32_e32 v83, 0xffff0000, v83
	v_lshlrev_b32_e32 v98, 16, v84
	v_and_b32_e32 v99, 0xffff0000, v84
	v_lshlrev_b32_e32 v84, 16, v85
	v_and_b32_e32 v85, 0xffff0000, v85
	v_pk_fma_f32 v[78:79], v[78:79], v[88:89], v[82:83]
	v_pk_fma_f32 v[76:77], v[76:77], v[86:87], v[96:97]
	v_pk_fma_f32 v[82:83], v[74:75], v[92:93], v[84:85]
	v_pk_fma_f32 v[74:75], v[72:73], v[90:91], v[98:99]
	v_cvt_pk_bf16_f32 v72, v76, v77
	v_cvt_pk_bf16_f32 v73, v78, v79
	v_cvt_pk_bf16_f32 v74, v74, v75
	v_cvt_pk_bf16_f32 v75, v82, v83
	global_store_dwordx4 v[94:95], v[72:75], off
	s_nop 1
	v_lshl_add_u64 v[72:73], s[10:11], 0, v[80:81]
	v_lshl_add_u64 v[80:81], s[16:17], 0, v[80:81]
	s_waitcnt vmcnt(15)
	v_mov_b64_e32 v[72:73], v[174:175]
	v_mov_b64_e32 v[74:75], v[176:177]
	v_lshlrev_b32_e32 v76, 16, v72
	v_and_b32_e32 v77, 0xffff0000, v72
	v_lshlrev_b32_e32 v78, 16, v73
	v_and_b32_e32 v79, 0xffff0000, v73
	v_lshlrev_b32_e32 v82, 16, v74
	v_and_b32_e32 v83, 0xffff0000, v74
	v_lshlrev_b32_e32 v84, 16, v75
	v_and_b32_e32 v85, 0xffff0000, v75
	s_waitcnt vmcnt(14)
	v_mov_b64_e32 v[72:73], v[178:179]
	v_mov_b64_e32 v[74:75], v[180:181]
	s_add_u32 s60, s10, 0x50000
	s_addc_u32 s61, s11, 0
	s_add_u32 s62, s16, 0x50000
	s_addc_u32 s63, s17, 0
	global_load_dwordx4 v[166:169], v136, s[60:61]
	global_load_dwordx4 v[170:173], v136, s[62:63]
	global_load_dwordx4 v[174:177], v136, s[60:61] offset:256
	global_load_dwordx4 v[178:181], v136, s[62:63] offset:256
	v_lshlrev_b32_e32 v86, 16, v72
	v_and_b32_e32 v87, 0xffff0000, v72
	v_lshlrev_b32_e32 v72, 16, v73
	v_and_b32_e32 v73, 0xffff0000, v73
	v_lshlrev_b32_e32 v88, 16, v74
	v_and_b32_e32 v89, 0xffff0000, v74
	v_lshlrev_b32_e32 v74, 16, v75
	v_and_b32_e32 v75, 0xffff0000, v75
	v_pk_fma_f32 v[70:71], v[70:71], v[78:79], v[72:73]
	v_pk_fma_f32 v[68:69], v[68:69], v[76:77], v[86:87]
	v_pk_fma_f32 v[72:73], v[66:67], v[84:85], v[74:75]
	v_pk_fma_f32 v[66:67], v[64:65], v[82:83], v[88:89]
	v_cvt_pk_bf16_f32 v64, v68, v69
	v_cvt_pk_bf16_f32 v65, v70, v71
	v_cvt_pk_bf16_f32 v66, v66, v67
	v_cvt_pk_bf16_f32 v67, v72, v73
	global_store_dwordx4 v[80:81], v[64:67], off
	v_lshl_add_u64 v[68:69], v[136:137], 0, s[90:91]
	s_nop 0
	v_lshl_add_u64 v[64:65], s[10:11], 0, v[68:69]
	v_lshl_add_u64 v[68:69], s[16:17], 0, v[68:69]
	s_waitcnt vmcnt(16)
	v_mov_b64_e32 v[64:65], v[182:183]
	v_mov_b64_e32 v[66:67], v[184:185]
	v_lshlrev_b32_e32 v70, 16, v64
	v_and_b32_e32 v71, 0xffff0000, v64
	v_lshlrev_b32_e32 v72, 16, v65
	v_and_b32_e32 v73, 0xffff0000, v65
	v_lshlrev_b32_e32 v74, 16, v66
	v_and_b32_e32 v75, 0xffff0000, v66
	v_lshlrev_b32_e32 v76, 16, v67
	v_and_b32_e32 v77, 0xffff0000, v67
	s_waitcnt vmcnt(15)
	v_mov_b64_e32 v[64:65], v[186:187]
	v_mov_b64_e32 v[66:67], v[188:189]
	v_lshlrev_b32_e32 v78, 16, v64
	v_and_b32_e32 v79, 0xffff0000, v64
	v_lshlrev_b32_e32 v64, 16, v65
	v_and_b32_e32 v65, 0xffff0000, v65
	v_lshlrev_b32_e32 v80, 16, v66
	v_and_b32_e32 v81, 0xffff0000, v66
	v_lshlrev_b32_e32 v66, 16, v67
	v_and_b32_e32 v67, 0xffff0000, v67
	v_pk_fma_f32 v[62:63], v[62:63], v[72:73], v[64:65]
	v_pk_fma_f32 v[60:61], v[60:61], v[70:71], v[78:79]
	v_pk_fma_f32 v[64:65], v[58:59], v[76:77], v[66:67]
	v_pk_fma_f32 v[58:59], v[56:57], v[74:75], v[80:81]
	v_cvt_pk_bf16_f32 v56, v60, v61
	v_cvt_pk_bf16_f32 v57, v62, v63
	v_cvt_pk_bf16_f32 v58, v58, v59
	v_cvt_pk_bf16_f32 v59, v64, v65
	v_lshl_add_u64 v[60:61], v[136:137], 0, s[0:1]
	global_store_dwordx4 v[68:69], v[56:59], off
	s_mov_b64 s[0:1], 0x48000
	s_nop 0
	v_lshl_add_u64 v[56:57], s[10:11], 0, v[60:61]
	v_lshl_add_u64 v[60:61], s[16:17], 0, v[60:61]
	s_waitcnt vmcnt(15)
	v_mov_b64_e32 v[56:57], v[190:191]
	v_mov_b64_e32 v[58:59], v[192:193]
	v_lshlrev_b32_e32 v62, 16, v56
	v_and_b32_e32 v63, 0xffff0000, v56
	v_lshlrev_b32_e32 v64, 16, v57
	v_and_b32_e32 v65, 0xffff0000, v57
	v_lshlrev_b32_e32 v66, 16, v58
	v_and_b32_e32 v67, 0xffff0000, v58
	v_lshlrev_b32_e32 v68, 16, v59
	v_and_b32_e32 v69, 0xffff0000, v59
	s_waitcnt vmcnt(14)
	v_mov_b64_e32 v[56:57], v[194:195]
	v_mov_b64_e32 v[58:59], v[196:197]
	s_add_u32 s60, s10, 0x58000
	s_addc_u32 s61, s11, 0
	s_add_u32 s62, s16, 0x58000
	s_addc_u32 s63, s17, 0
	global_load_dwordx4 v[182:185], v136, s[60:61]
	global_load_dwordx4 v[186:189], v136, s[62:63]
	global_load_dwordx4 v[190:193], v136, s[60:61] offset:256
	global_load_dwordx4 v[194:197], v136, s[62:63] offset:256
	v_lshlrev_b32_e32 v70, 16, v56
	v_and_b32_e32 v71, 0xffff0000, v56
	v_lshlrev_b32_e32 v56, 16, v57
	v_and_b32_e32 v57, 0xffff0000, v57
	v_lshlrev_b32_e32 v72, 16, v58
	v_and_b32_e32 v73, 0xffff0000, v58
	v_lshlrev_b32_e32 v58, 16, v59
	v_and_b32_e32 v59, 0xffff0000, v59
	v_pk_fma_f32 v[54:55], v[54:55], v[64:65], v[56:57]
	v_pk_fma_f32 v[52:53], v[52:53], v[62:63], v[70:71]
	v_pk_fma_f32 v[56:57], v[50:51], v[68:69], v[58:59]
	v_pk_fma_f32 v[50:51], v[48:49], v[66:67], v[72:73]
	v_cvt_pk_bf16_f32 v48, v52, v53
	v_cvt_pk_bf16_f32 v49, v54, v55
	v_cvt_pk_bf16_f32 v50, v50, v51
	v_cvt_pk_bf16_f32 v51, v56, v57
	v_lshl_add_u64 v[52:53], v[136:137], 0, s[0:1]
	global_store_dwordx4 v[60:61], v[48:51], off
	s_mov_b64 s[0:1], 0x48100
	s_nop 0
	v_lshl_add_u64 v[48:49], s[10:11], 0, v[52:53]
	v_lshl_add_u64 v[52:53], s[16:17], 0, v[52:53]
	s_waitcnt vmcnt(16)
	v_mov_b64_e32 v[48:49], v[198:199]
	v_mov_b64_e32 v[50:51], v[200:201]
	v_lshlrev_b32_e32 v54, 16, v48
	v_and_b32_e32 v55, 0xffff0000, v48
	v_lshlrev_b32_e32 v56, 16, v49
	v_and_b32_e32 v57, 0xffff0000, v49
	v_lshlrev_b32_e32 v58, 16, v50
	v_and_b32_e32 v59, 0xffff0000, v50
	v_lshlrev_b32_e32 v60, 16, v51
	v_and_b32_e32 v61, 0xffff0000, v51
	s_waitcnt vmcnt(15)
; __device__ __forceinline__ u32x4 pack8(const f32x4 a, const f32x4 b) { u32x4 w; w.x = cvt_pk_bf16(a[0], a[1]); w.y = cvt_pk_bf16(a[2], a[3]); w.z = cvt_pk_bf16(b[0], b[1]); w.w = cvt_pk_bf16(b[2], b[3]); return w; }
; #define G opaque_s(G0)
;     __device__ __forceinline__ void operator()(const f32x4 (&acc)[2][2][4][2], const Unit& u, int wr, int wc, int fr, int fq) const {
;         const int row0 = u.pm * BM + wr * 64 + fr, col0 = u.pn * BM + wc * 32 + 8 * fq;
; #pragma unroll
;         for (int ai = 0; ai < 2; ++ai)
; #pragma unroll
;             for (int m = 0; m < 4; ++m) { if ((m & 1) == 0) asm volatile("" ::: "memory"); const int row = row0 + ai * HALF + m * 16;
; #pragma unroll
;                 for (int bj = 0; bj < 2; ++bj) { const size_t off = (size_t)row * 1024 + col0 + bj * HALF;
;                     f32x4 g0, g1; unpack8(*(const u32x4*)(G + off), g0, g1);
;                     f32x4 o0 = acc[ai][bj][m][0] * g0, o1 = acc[ai][bj][m][1] * g1;
;                     if (!first) { f32x4 p0, p1; unpack8(*(const u32x4*)(Mg + off), p0, p1); o0 = o0 + p0; o1 = o1 + p1; }
;                     *(u32x4*)(Mg + off) = pack8(o0, o1); } }
	v_mov_b64_e32 v[48:49], v[202:203]
	v_mov_b64_e32 v[50:51], v[204:205]
	v_lshlrev_b32_e32 v62, 16, v48
	v_and_b32_e32 v63, 0xffff0000, v48
	v_lshlrev_b32_e32 v48, 16, v49
	v_and_b32_e32 v49, 0xffff0000, v49
	v_lshlrev_b32_e32 v64, 16, v50
	v_and_b32_e32 v65, 0xffff0000, v50
	v_lshlrev_b32_e32 v50, 16, v51
	v_and_b32_e32 v51, 0xffff0000, v51
	v_pk_fma_f32 v[46:47], v[46:47], v[56:57], v[48:49]
	v_pk_fma_f32 v[44:45], v[44:45], v[54:55], v[62:63]
	v_pk_fma_f32 v[48:49], v[42:43], v[60:61], v[50:51]
	v_pk_fma_f32 v[42:43], v[40:41], v[58:59], v[64:65]
	v_cvt_pk_bf16_f32 v40, v44, v45
	v_cvt_pk_bf16_f32 v41, v46, v47
	v_cvt_pk_bf16_f32 v42, v42, v43
	v_cvt_pk_bf16_f32 v43, v48, v49
	v_lshl_add_u64 v[44:45], v[136:137], 0, s[0:1]
	global_store_dwordx4 v[52:53], v[40:43], off
	s_mov_b64 s[0:1], 0x50000
	s_nop 0
	v_lshl_add_u64 v[40:41], s[10:11], 0, v[44:45]
	v_lshl_add_u64 v[44:45], s[16:17], 0, v[44:45]
	s_waitcnt vmcnt(15)
	v_mov_b64_e32 v[40:41], v[206:207]
	v_mov_b64_e32 v[42:43], v[208:209]
	v_lshlrev_b32_e32 v46, 16, v40
	v_and_b32_e32 v47, 0xffff0000, v40
	v_lshlrev_b32_e32 v48, 16, v41
	v_and_b32_e32 v49, 0xffff0000, v41
	v_lshlrev_b32_e32 v50, 16, v42
	v_and_b32_e32 v51, 0xffff0000, v42
	v_lshlrev_b32_e32 v52, 16, v43
	v_and_b32_e32 v53, 0xffff0000, v43
	s_waitcnt vmcnt(14)
	v_mov_b64_e32 v[40:41], v[210:211]
	v_mov_b64_e32 v[42:43], v[212:213]
	v_lshlrev_b32_e32 v54, 16, v40
	v_and_b32_e32 v55, 0xffff0000, v40
	v_lshlrev_b32_e32 v40, 16, v41
	v_and_b32_e32 v41, 0xffff0000, v41
	v_lshlrev_b32_e32 v56, 16, v42
	v_and_b32_e32 v57, 0xffff0000, v42
	v_lshlrev_b32_e32 v42, 16, v43
	v_and_b32_e32 v43, 0xffff0000, v43
	v_pk_fma_f32 v[38:39], v[38:39], v[48:49], v[40:41]
	v_pk_fma_f32 v[36:37], v[36:37], v[46:47], v[54:55]
	v_pk_fma_f32 v[40:41], v[34:35], v[52:53], v[42:43]
	v_pk_fma_f32 v[34:35], v[32:33], v[50:51], v[56:57]
	v_cvt_pk_bf16_f32 v32, v36, v37
	v_cvt_pk_bf16_f32 v33, v38, v39
	v_cvt_pk_bf16_f32 v34, v34, v35
	v_cvt_pk_bf16_f32 v35, v40, v41
	global_store_dwordx4 v[44:45], v[32:35], off
	v_lshl_add_u64 v[36:37], v[136:137], 0, s[0:1]
	s_mov_b64 s[0:1], 0x50100
	v_lshl_add_u64 v[32:33], s[10:11], 0, v[36:37]
	v_lshl_add_u64 v[36:37], s[16:17], 0, v[36:37]
	s_waitcnt vmcnt(12)
	v_mov_b64_e32 v[32:33], v[166:167]
	v_mov_b64_e32 v[34:35], v[168:169]
	v_lshlrev_b32_e32 v38, 16, v32
	v_and_b32_e32 v39, 0xffff0000, v32
	v_lshlrev_b32_e32 v40, 16, v33
	v_and_b32_e32 v41, 0xffff0000, v33
	v_lshlrev_b32_e32 v42, 16, v34
	v_and_b32_e32 v43, 0xffff0000, v34
	v_lshlrev_b32_e32 v44, 16, v35
	v_and_b32_e32 v45, 0xffff0000, v35
	s_waitcnt vmcnt(11)
	v_mov_b64_e32 v[32:33], v[170:171]
	v_mov_b64_e32 v[34:35], v[172:173]
	v_lshlrev_b32_e32 v46, 16, v32
	v_and_b32_e32 v47, 0xffff0000, v32
	v_lshlrev_b32_e32 v32, 16, v33
	v_and_b32_e32 v33, 0xffff0000, v33
	v_lshlrev_b32_e32 v48, 16, v34
	v_and_b32_e32 v49, 0xffff0000, v34
	v_lshlrev_b32_e32 v34, 16, v35
	v_and_b32_e32 v35, 0xffff0000, v35
	v_pk_fma_f32 v[30:31], v[30:31], v[40:41], v[32:33]
	v_pk_fma_f32 v[28:29], v[28:29], v[38:39], v[46:47]
	v_pk_fma_f32 v[32:33], v[26:27], v[44:45], v[34:35]
	v_pk_fma_f32 v[26:27], v[24:25], v[42:43], v[48:49]
	v_cvt_pk_bf16_f32 v24, v28, v29
	v_cvt_pk_bf16_f32 v25, v30, v31
	v_cvt_pk_bf16_f32 v26, v26, v27
	v_cvt_pk_bf16_f32 v27, v32, v33
	v_lshl_add_u64 v[28:29], v[136:137], 0, s[0:1]
	global_store_dwordx4 v[36:37], v[24:27], off
	s_mov_b64 s[0:1], 0x58100
	s_nop 0
	v_lshl_add_u64 v[24:25], s[10:11], 0, v[28:29]
	v_lshl_add_u64 v[28:29], s[16:17], 0, v[28:29]
	s_waitcnt vmcnt(11)
; __device__ __forceinline__ u32x4 pack8(const f32x4 a, const f32x4 b) { u32x4 w; w.x = cvt_pk_bf16(a[0], a[1]); w.y = cvt_pk_bf16(a[2], a[3]); w.z = cvt_pk_bf16(b[0], b[1]); w.w = cvt_pk_bf16(b[2], b[3]); return w; }
; #define G opaque_s(G0)
;     __device__ __forceinline__ void operator()(const f32x4 (&acc)[2][2][4][2], const Unit& u, int wr, int wc, int fr, int fq) const {
;         const int row0 = u.pm * BM + wr * 64 + fr, col0 = u.pn * BM + wc * 32 + 8 * fq;
; #pragma unroll
;         for (int ai = 0; ai < 2; ++ai)
; #pragma unroll
;             for (int m = 0; m < 4; ++m) { if ((m & 1) == 0) asm volatile("" ::: "memory"); const int row = row0 + ai * HALF + m * 16;
; #pragma unroll
;                 for (int bj = 0; bj < 2; ++bj) { const size_t off = (size_t)row * 1024 + col0 + bj * HALF;
;                     f32x4 g0, g1; unpack8(*(const u32x4*)(G + off), g0, g1);
;                     f32x4 o0 = acc[ai][bj][m][0] * g0, o1 = acc[ai][bj][m][1] * g1;
;                     if (!first) { f32x4 p0, p1; unpack8(*(const u32x4*)(Mg + off), p0, p1); o0 = o0 + p0; o1 = o1 + p1; }
;                     *(u32x4*)(Mg + off) = pack8(o0, o1); } }
	v_mov_b64_e32 v[24:25], v[174:175]
	v_mov_b64_e32 v[26:27], v[176:177]
	v_lshlrev_b32_e32 v30, 16, v24
	v_and_b32_e32 v31, 0xffff0000, v24
	v_lshlrev_b32_e32 v32, 16, v25
	v_and_b32_e32 v33, 0xffff0000, v25
	v_lshlrev_b32_e32 v34, 16, v26
	v_and_b32_e32 v35, 0xffff0000, v26
	v_lshlrev_b32_e32 v36, 16, v27
	v_and_b32_e32 v37, 0xffff0000, v27
	s_waitcnt vmcnt(10)
	v_mov_b64_e32 v[24:25], v[178:179]
	v_mov_b64_e32 v[26:27], v[180:181]
	v_lshlrev_b32_e32 v38, 16, v24
	v_and_b32_e32 v39, 0xffff0000, v24
	v_lshlrev_b32_e32 v24, 16, v25
	v_and_b32_e32 v25, 0xffff0000, v25
	v_lshlrev_b32_e32 v40, 16, v26
	v_and_b32_e32 v41, 0xffff0000, v26
	v_lshlrev_b32_e32 v26, 16, v27
	v_and_b32_e32 v27, 0xffff0000, v27
	v_pk_fma_f32 v[22:23], v[22:23], v[32:33], v[24:25]
	v_pk_fma_f32 v[20:21], v[20:21], v[30:31], v[38:39]
	v_pk_fma_f32 v[24:25], v[18:19], v[36:37], v[26:27]
	v_pk_fma_f32 v[18:19], v[16:17], v[34:35], v[40:41]
	v_cvt_pk_bf16_f32 v16, v20, v21
	v_cvt_pk_bf16_f32 v17, v22, v23
	v_cvt_pk_bf16_f32 v18, v18, v19
	v_cvt_pk_bf16_f32 v19, v24, v25
	v_lshl_add_u64 v[20:21], v[136:137], 0, s[78:79]
	global_store_dwordx4 v[28:29], v[16:19], off
	s_nop 1
	v_lshl_add_u64 v[16:17], s[10:11], 0, v[20:21]
	v_lshl_add_u64 v[20:21], s[16:17], 0, v[20:21]
	s_waitcnt vmcnt(8)
	v_mov_b64_e32 v[16:17], v[182:183]
	v_mov_b64_e32 v[18:19], v[184:185]
	v_lshlrev_b32_e32 v22, 16, v16
	v_and_b32_e32 v23, 0xffff0000, v16
	v_lshlrev_b32_e32 v24, 16, v17
	v_and_b32_e32 v25, 0xffff0000, v17
	v_lshlrev_b32_e32 v26, 16, v18
	v_and_b32_e32 v27, 0xffff0000, v18
	v_lshlrev_b32_e32 v28, 16, v19
	v_and_b32_e32 v29, 0xffff0000, v19
	s_waitcnt vmcnt(7)
	v_mov_b64_e32 v[16:17], v[186:187]
	v_mov_b64_e32 v[18:19], v[188:189]
	v_lshlrev_b32_e32 v30, 16, v16
	v_and_b32_e32 v31, 0xffff0000, v16
	v_lshlrev_b32_e32 v16, 16, v17
	v_and_b32_e32 v17, 0xffff0000, v17
	v_lshlrev_b32_e32 v32, 16, v18
	v_and_b32_e32 v33, 0xffff0000, v18
	v_lshlrev_b32_e32 v18, 16, v19
	v_and_b32_e32 v19, 0xffff0000, v19
	v_pk_fma_f32 v[14:15], v[14:15], v[24:25], v[16:17]
	v_pk_fma_f32 v[12:13], v[12:13], v[22:23], v[30:31]
	v_pk_fma_f32 v[16:17], v[10:11], v[28:29], v[18:19]
	v_pk_fma_f32 v[10:11], v[8:9], v[26:27], v[32:33]
	v_cvt_pk_bf16_f32 v8, v12, v13
	v_cvt_pk_bf16_f32 v9, v14, v15
	v_cvt_pk_bf16_f32 v10, v10, v11
	v_cvt_pk_bf16_f32 v11, v16, v17
	v_lshl_add_u64 v[12:13], v[136:137], 0, s[0:1]
	global_store_dwordx4 v[20:21], v[8:11], off
	s_mov_b64 s[0:1], -1
	s_nop 0
	v_lshl_add_u64 v[8:9], s[10:11], 0, v[12:13]
	v_lshl_add_u64 v[12:13], s[16:17], 0, v[12:13]
	s_waitcnt vmcnt(7)
	v_mov_b64_e32 v[8:9], v[190:191]
	v_mov_b64_e32 v[10:11], v[192:193]
	v_lshlrev_b32_e32 v14, 16, v8
	v_and_b32_e32 v15, 0xffff0000, v8
	v_lshlrev_b32_e32 v16, 16, v9
	v_and_b32_e32 v17, 0xffff0000, v9
	v_lshlrev_b32_e32 v18, 16, v10
	v_and_b32_e32 v19, 0xffff0000, v10
	v_lshlrev_b32_e32 v20, 16, v11
	v_and_b32_e32 v21, 0xffff0000, v11
	s_waitcnt vmcnt(6)
	v_mov_b64_e32 v[8:9], v[194:195]
	v_mov_b64_e32 v[10:11], v[196:197]
	v_lshlrev_b32_e32 v22, 16, v8
	v_and_b32_e32 v23, 0xffff0000, v8
	v_lshlrev_b32_e32 v8, 16, v9
	v_and_b32_e32 v9, 0xffff0000, v9
	v_lshlrev_b32_e32 v24, 16, v10
	v_and_b32_e32 v25, 0xffff0000, v10
	v_lshlrev_b32_e32 v10, 16, v11
	v_and_b32_e32 v11, 0xffff0000, v11
	v_pk_fma_f32 v[6:7], v[6:7], v[16:17], v[8:9]
	v_pk_fma_f32 v[4:5], v[4:5], v[14:15], v[22:23]
	v_pk_fma_f32 v[8:9], v[2:3], v[20:21], v[10:11]
	v_pk_fma_f32 v[2:3], v[0:1], v[18:19], v[24:25]
	v_cvt_pk_bf16_f32 v0, v4, v5
	v_cvt_pk_bf16_f32 v1, v6, v7
	v_cvt_pk_bf16_f32 v2, v2, v3
	v_cvt_pk_bf16_f32 v3, v8, v9
	global_store_dwordx4 v[12:13], v[0:3], off
	s_cbranch_vccnz .LBB0_1499
	s_andn2_b64 vcc, exec, s[8:9]
	s_cbranch_vccnz .LBB0_1498
	s_barrier
	s_branch .LBB0_1498

; __device__ __forceinline__ u32x4 pack8(const f32x4 a, const f32x4 b) { u32x4 w; w.x = cvt_pk_bf16(a[0], a[1]); w.y = cvt_pk_bf16(a[2], a[3]); w.z = cvt_pk_bf16(b[0], b[1]); w.w = cvt_pk_bf16(b[2], b[3]); return w; }
; #define G opaque_s(G0)
;     __device__ __forceinline__ void operator()(const f32x4 (&acc)[2][2][4][2], const Unit& u, int wr, int wc, int fr, int fq) const {
;         const int row0 = u.pm * BM + wr * 64 + fr, col0 = u.pn * BM + wc * 32 + 8 * fq;
; #pragma unroll
;         for (int ai = 0; ai < 2; ++ai)
; #pragma unroll
;             for (int m = 0; m < 4; ++m) { if ((m & 1) == 0) asm volatile("" ::: "memory"); const int row = row0 + ai * HALF + m * 16;
; #pragma unroll
;                 for (int bj = 0; bj < 2; ++bj) { const size_t off = (size_t)row * 1024 + col0 + bj * HALF;
;                     f32x4 g0, g1; unpack8(*(const u32x4*)(G + off), g0, g1);
;                     f32x4 o0 = acc[ai][bj][m][0] * g0, o1 = acc[ai][bj][m][1] * g1;
;                     if (!first) { f32x4 p0, p1; unpack8(*(const u32x4*)(Mg + off), p0, p1); o0 = o0 + p0; o1 = o1 + p1; }
;                     *(u32x4*)(Mg + off) = pack8(o0, o1); } }
.LBB0_1560:
	v_lshl_add_u32 v140, s0, 8, v144
	v_lshl_or_b32 v138, s1, 8, v146
	v_ashrrev_i32_e32 v141, 31, v140
	v_ashrrev_i32_e32 v139, 31, v138
	v_lshlrev_b64 v[136:137], 10, v[140:141]
	v_lshl_add_u64 v[136:137], v[136:137], 0, v[138:139]
	v_lshlrev_b64 v[136:137], 1, v[136:137]
	v_lshl_add_u64 v[148:149], s[8:9], 0, v[136:137]
	s_mov_b64 s[60:61], s[8:9]
	s_mov_b64 s[62:63], s[10:11]
	global_load_dwordx4 v[166:169], v136, s[60:61]
	global_load_dwordx4 v[170:173], v136, s[62:63]
	global_load_dwordx4 v[174:177], v136, s[60:61] offset:256
	global_load_dwordx4 v[178:181], v136, s[62:63] offset:256
	s_add_u32 s60, s8, 0x8000
	s_addc_u32 s61, s9, 0
	s_add_u32 s62, s10, 0x8000
	s_addc_u32 s63, s11, 0
	global_load_dwordx4 v[182:185], v136, s[60:61]
	global_load_dwordx4 v[186:189], v136, s[62:63]
	global_load_dwordx4 v[190:193], v136, s[60:61] offset:256
	global_load_dwordx4 v[194:197], v136, s[62:63] offset:256
	s_add_u32 s60, s8, 0x10000
	s_addc_u32 s61, s9, 0
	s_add_u32 s62, s10, 0x10000
	s_addc_u32 s63, s11, 0
	global_load_dwordx4 v[198:201], v136, s[60:61]
	global_load_dwordx4 v[202:205], v136, s[62:63]
	global_load_dwordx4 v[206:209], v136, s[60:61] offset:256
	global_load_dwordx4 v[210:213], v136, s[62:63] offset:256
	v_lshl_add_u64 v[160:161], s[10:11], 0, v[136:137]
	s_mov_b64 s[0:1], 0x40100
	s_andn2_b64 vcc, exec, s[4:5]
	s_waitcnt vmcnt(11)
	v_mov_b64_e32 v[148:149], v[166:167]
	v_mov_b64_e32 v[150:151], v[168:169]
	v_lshlrev_b32_e32 v152, 16, v148
	v_and_b32_e32 v153, 0xffff0000, v148
	v_lshlrev_b32_e32 v154, 16, v149
	v_and_b32_e32 v155, 0xffff0000, v149
	v_lshlrev_b32_e32 v156, 16, v150
	v_and_b32_e32 v157, 0xffff0000, v150
	v_lshlrev_b32_e32 v158, 16, v151
	v_and_b32_e32 v159, 0xffff0000, v151
	s_waitcnt vmcnt(10)
	v_mov_b64_e32 v[148:149], v[170:171]
	v_mov_b64_e32 v[150:151], v[172:173]
	v_lshlrev_b32_e32 v162, 16, v148
	v_and_b32_e32 v163, 0xffff0000, v148
	v_lshlrev_b32_e32 v148, 16, v149
	v_and_b32_e32 v149, 0xffff0000, v149
	v_lshlrev_b32_e32 v164, 16, v150
	v_and_b32_e32 v165, 0xffff0000, v150
	v_lshlrev_b32_e32 v150, 16, v151
	v_and_b32_e32 v151, 0xffff0000, v151
	v_pk_fma_f32 v[128:129], v[128:129], v[154:155], v[148:149]
	v_pk_fma_f32 v[126:127], v[126:127], v[152:153], v[162:163]
	v_pk_fma_f32 v[148:149], v[124:125], v[158:159], v[150:151]
	v_pk_fma_f32 v[124:125], v[122:123], v[156:157], v[164:165]
	v_cvt_pk_bf16_f32 v122, v126, v127
	v_cvt_pk_bf16_f32 v123, v128, v129
	v_cvt_pk_bf16_f32 v124, v124, v125
	v_cvt_pk_bf16_f32 v125, v148, v149
	v_or_b32_e32 v126, 0x100, v136
	v_mov_b32_e32 v127, v137
	global_store_dwordx4 v[160:161], v[122:125], off
	s_nop 1
	v_lshl_add_u64 v[122:123], s[8:9], 0, v[126:127]
	v_lshl_add_u64 v[126:127], s[10:11], 0, v[126:127]
	s_waitcnt vmcnt(10)
	v_mov_b64_e32 v[122:123], v[174:175]
	v_mov_b64_e32 v[124:125], v[176:177]
	v_lshlrev_b32_e32 v128, 16, v122
	v_and_b32_e32 v129, 0xffff0000, v122
	v_lshlrev_b32_e32 v148, 16, v123
	v_and_b32_e32 v149, 0xffff0000, v123
	v_lshlrev_b32_e32 v150, 16, v124
	v_and_b32_e32 v151, 0xffff0000, v124
	v_lshlrev_b32_e32 v152, 16, v125
	v_and_b32_e32 v153, 0xffff0000, v125
	s_waitcnt vmcnt(9)
	v_mov_b64_e32 v[122:123], v[178:179]
	v_mov_b64_e32 v[124:125], v[180:181]
	s_add_u32 s60, s8, 0x18000
	s_addc_u32 s61, s9, 0
	s_add_u32 s62, s10, 0x18000
	s_addc_u32 s63, s11, 0
	global_load_dwordx4 v[166:169], v136, s[60:61]
	global_load_dwordx4 v[170:173], v136, s[62:63]
	global_load_dwordx4 v[174:177], v136, s[60:61] offset:256
	global_load_dwordx4 v[178:181], v136, s[62:63] offset:256
	v_lshlrev_b32_e32 v154, 16, v122
	v_and_b32_e32 v155, 0xffff0000, v122
	v_lshlrev_b32_e32 v122, 16, v123
	v_and_b32_e32 v123, 0xffff0000, v123
	v_lshlrev_b32_e32 v156, 16, v124
	v_and_b32_e32 v157, 0xffff0000, v124
	v_lshlrev_b32_e32 v124, 16, v125
	v_and_b32_e32 v125, 0xffff0000, v125
	v_pk_fma_f32 v[120:121], v[120:121], v[148:149], v[122:123]
	v_pk_fma_f32 v[118:119], v[118:119], v[128:129], v[154:155]
	v_pk_fma_f32 v[122:123], v[116:117], v[152:153], v[124:125]
	v_pk_fma_f32 v[116:117], v[114:115], v[150:151], v[156:157]
	v_cvt_pk_bf16_f32 v114, v118, v119
	v_cvt_pk_bf16_f32 v115, v120, v121
	v_cvt_pk_bf16_f32 v116, v116, v117
	v_cvt_pk_bf16_f32 v117, v122, v123
	global_store_dwordx4 v[126:127], v[114:117], off
	s_nop 1
	v_or_b32_e32 v114, 16, v140
	v_ashrrev_i32_e32 v115, 31, v114
	v_lshlrev_b64 v[114:115], 10, v[114:115]
	v_lshl_add_u64 v[114:115], v[114:115], 0, v[138:139]
	v_lshlrev_b64 v[114:115], 1, v[114:115]
	v_lshl_add_u64 v[116:117], s[8:9], 0, v[114:115]
	v_lshl_add_u64 v[128:129], s[10:11], 0, v[114:115]
	v_or_b32_e32 v114, 0x100, v114
	s_waitcnt vmcnt(13)
	v_mov_b64_e32 v[116:117], v[182:183]
	v_mov_b64_e32 v[118:119], v[184:185]
	v_lshlrev_b32_e32 v120, 16, v116
	v_and_b32_e32 v121, 0xffff0000, v116
	v_lshlrev_b32_e32 v122, 16, v117
	v_and_b32_e32 v123, 0xffff0000, v117
	v_lshlrev_b32_e32 v124, 16, v118
	v_and_b32_e32 v125, 0xffff0000, v118
	v_lshlrev_b32_e32 v126, 16, v119
	v_and_b32_e32 v127, 0xffff0000, v119
	s_waitcnt vmcnt(12)
	v_mov_b64_e32 v[116:117], v[186:187]
	v_mov_b64_e32 v[118:119], v[188:189]
	v_lshlrev_b32_e32 v148, 16, v116
	v_and_b32_e32 v149, 0xffff0000, v116
	v_lshlrev_b32_e32 v116, 16, v117
	v_and_b32_e32 v117, 0xffff0000, v117
	v_lshlrev_b32_e32 v150, 16, v118
	v_and_b32_e32 v151, 0xffff0000, v118
	v_lshlrev_b32_e32 v118, 16, v119
	v_and_b32_e32 v119, 0xffff0000, v119
	v_pk_fma_f32 v[110:111], v[110:111], v[122:123], v[116:117]
	v_pk_fma_f32 v[108:109], v[108:109], v[120:121], v[148:149]
	v_pk_fma_f32 v[116:117], v[106:107], v[126:127], v[118:119]
	v_pk_fma_f32 v[106:107], v[104:105], v[124:125], v[150:151]
	v_cvt_pk_bf16_f32 v104, v108, v109
	v_cvt_pk_bf16_f32 v105, v110, v111
	v_cvt_pk_bf16_f32 v106, v106, v107
	v_cvt_pk_bf16_f32 v107, v116, v117
	global_store_dwordx4 v[128:129], v[104:107], off
	s_nop 1
	v_lshl_add_u64 v[104:105], s[8:9], 0, v[114:115]
	v_lshl_add_u64 v[114:115], s[10:11], 0, v[114:115]
	s_waitcnt vmcnt(12)
; __device__ __forceinline__ u32x4 pack8(const f32x4 a, const f32x4 b) { u32x4 w; w.x = cvt_pk_bf16(a[0], a[1]); w.y = cvt_pk_bf16(a[2], a[3]); w.z = cvt_pk_bf16(b[0], b[1]); w.w = cvt_pk_bf16(b[2], b[3]); return w; }
; #define G opaque_s(G0)
;     __device__ __forceinline__ void operator()(const f32x4 (&acc)[2][2][4][2], const Unit& u, int wr, int wc, int fr, int fq) const {
;         const int row0 = u.pm * BM + wr * 64 + fr, col0 = u.pn * BM + wc * 32 + 8 * fq;
; #pragma unroll
;         for (int ai = 0; ai < 2; ++ai)
; #pragma unroll
;             for (int m = 0; m < 4; ++m) { if ((m & 1) == 0) asm volatile("" ::: "memory"); const int row = row0 + ai * HALF + m * 16;
; #pragma unroll
;                 for (int bj = 0; bj < 2; ++bj) { const size_t off = (size_t)row * 1024 + col0 + bj * HALF;
;                     f32x4 g0, g1; unpack8(*(const u32x4*)(G + off), g0, g1);
;                     f32x4 o0 = acc[ai][bj][m][0] * g0, o1 = acc[ai][bj][m][1] * g1;
;                     if (!first) { f32x4 p0, p1; unpack8(*(const u32x4*)(Mg + off), p0, p1); o0 = o0 + p0; o1 = o1 + p1; }
;                     *(u32x4*)(Mg + off) = pack8(o0, o1); } }
	v_mov_b64_e32 v[104:105], v[190:191]
	v_mov_b64_e32 v[106:107], v[192:193]
	v_lshlrev_b32_e32 v108, 16, v104
	v_and_b32_e32 v109, 0xffff0000, v104
	v_lshlrev_b32_e32 v110, 16, v105
	v_and_b32_e32 v111, 0xffff0000, v105
	v_lshlrev_b32_e32 v116, 16, v106
	v_and_b32_e32 v117, 0xffff0000, v106
	v_lshlrev_b32_e32 v118, 16, v107
	v_and_b32_e32 v119, 0xffff0000, v107
	s_waitcnt vmcnt(11)
	v_mov_b64_e32 v[104:105], v[194:195]
	v_mov_b64_e32 v[106:107], v[196:197]
	s_add_u32 s60, s8, 0x40000
	s_addc_u32 s61, s9, 0
	s_add_u32 s62, s10, 0x40000
	s_addc_u32 s63, s11, 0
	global_load_dwordx4 v[182:185], v136, s[60:61]
	global_load_dwordx4 v[186:189], v136, s[62:63]
	global_load_dwordx4 v[190:193], v136, s[60:61] offset:256
	global_load_dwordx4 v[194:197], v136, s[62:63] offset:256
	v_lshlrev_b32_e32 v120, 16, v104
	v_and_b32_e32 v121, 0xffff0000, v104
	v_lshlrev_b32_e32 v104, 16, v105
	v_and_b32_e32 v105, 0xffff0000, v105
	v_lshlrev_b32_e32 v122, 16, v106
	v_and_b32_e32 v123, 0xffff0000, v106
	v_lshlrev_b32_e32 v106, 16, v107
	v_and_b32_e32 v107, 0xffff0000, v107
	v_pk_fma_f32 v[102:103], v[102:103], v[110:111], v[104:105]
	v_pk_fma_f32 v[100:101], v[100:101], v[108:109], v[120:121]
	v_pk_fma_f32 v[104:105], v[98:99], v[118:119], v[106:107]
	v_pk_fma_f32 v[98:99], v[96:97], v[116:117], v[122:123]
	v_cvt_pk_bf16_f32 v96, v100, v101
	v_cvt_pk_bf16_f32 v97, v102, v103
	v_cvt_pk_bf16_f32 v98, v98, v99
	v_cvt_pk_bf16_f32 v99, v104, v105
	global_store_dwordx4 v[114:115], v[96:99], off
	s_nop 1
	v_or_b32_e32 v96, 32, v140
	v_ashrrev_i32_e32 v97, 31, v96
	v_lshlrev_b64 v[96:97], 10, v[96:97]
	v_lshl_add_u64 v[96:97], v[96:97], 0, v[138:139]
	v_lshlrev_b64 v[96:97], 1, v[96:97]
	v_lshl_add_u64 v[98:99], s[8:9], 0, v[96:97]
	v_lshl_add_u64 v[110:111], s[10:11], 0, v[96:97]
	v_or_b32_e32 v96, 0x100, v96
	s_waitcnt vmcnt(15)
	v_mov_b64_e32 v[98:99], v[198:199]
	v_mov_b64_e32 v[100:101], v[200:201]
	v_lshlrev_b32_e32 v102, 16, v98
	v_and_b32_e32 v103, 0xffff0000, v98
	v_lshlrev_b32_e32 v104, 16, v99
	v_and_b32_e32 v105, 0xffff0000, v99
	v_lshlrev_b32_e32 v106, 16, v100
	v_and_b32_e32 v107, 0xffff0000, v100
	v_lshlrev_b32_e32 v108, 16, v101
	v_and_b32_e32 v109, 0xffff0000, v101
	s_waitcnt vmcnt(14)
	v_mov_b64_e32 v[98:99], v[202:203]
	v_mov_b64_e32 v[100:101], v[204:205]
	v_lshlrev_b32_e32 v114, 16, v98
	v_and_b32_e32 v115, 0xffff0000, v98
	v_lshlrev_b32_e32 v98, 16, v99
	v_and_b32_e32 v99, 0xffff0000, v99
	v_lshlrev_b32_e32 v116, 16, v100
	v_and_b32_e32 v117, 0xffff0000, v100
	v_lshlrev_b32_e32 v100, 16, v101
	v_and_b32_e32 v101, 0xffff0000, v101
	v_pk_fma_f32 v[94:95], v[94:95], v[104:105], v[98:99]
	v_pk_fma_f32 v[92:93], v[92:93], v[102:103], v[114:115]
	v_pk_fma_f32 v[98:99], v[90:91], v[108:109], v[100:101]
	v_pk_fma_f32 v[90:91], v[88:89], v[106:107], v[116:117]
	v_cvt_pk_bf16_f32 v88, v92, v93
	v_cvt_pk_bf16_f32 v89, v94, v95
	v_cvt_pk_bf16_f32 v90, v90, v91
	v_cvt_pk_bf16_f32 v91, v98, v99
	global_store_dwordx4 v[110:111], v[88:91], off
	s_nop 1
	v_lshl_add_u64 v[88:89], s[8:9], 0, v[96:97]
	v_lshl_add_u64 v[96:97], s[10:11], 0, v[96:97]
	s_waitcnt vmcnt(14)
	v_mov_b64_e32 v[88:89], v[206:207]
	v_mov_b64_e32 v[90:91], v[208:209]
	v_lshlrev_b32_e32 v92, 16, v88
	v_and_b32_e32 v93, 0xffff0000, v88
	v_lshlrev_b32_e32 v94, 16, v89
	v_and_b32_e32 v95, 0xffff0000, v89
	v_lshlrev_b32_e32 v98, 16, v90
	v_and_b32_e32 v99, 0xffff0000, v90
	v_lshlrev_b32_e32 v100, 16, v91
	v_and_b32_e32 v101, 0xffff0000, v91
	s_waitcnt vmcnt(13)
	v_mov_b64_e32 v[88:89], v[210:211]
	v_mov_b64_e32 v[90:91], v[212:213]
	s_add_u32 s60, s8, 0x48000
	s_addc_u32 s61, s9, 0
	s_add_u32 s62, s10, 0x48000
	s_addc_u32 s63, s11, 0
	global_load_dwordx4 v[198:201], v136, s[60:61]
	global_load_dwordx4 v[202:205], v136, s[62:63]
	global_load_dwordx4 v[206:209], v136, s[60:61] offset:256
	global_load_dwordx4 v[210:213], v136, s[62:63] offset:256
	v_lshlrev_b32_e32 v102, 16, v88
	v_and_b32_e32 v103, 0xffff0000, v88
	v_lshlrev_b32_e32 v88, 16, v89
	v_and_b32_e32 v89, 0xffff0000, v89
	v_lshlrev_b32_e32 v104, 16, v90
	v_and_b32_e32 v105, 0xffff0000, v90
	v_lshlrev_b32_e32 v90, 16, v91
	v_and_b32_e32 v91, 0xffff0000, v91
	v_pk_fma_f32 v[86:87], v[86:87], v[94:95], v[88:89]
	v_pk_fma_f32 v[84:85], v[84:85], v[92:93], v[102:103]
	v_pk_fma_f32 v[88:89], v[82:83], v[100:101], v[90:91]
	v_pk_fma_f32 v[82:83], v[80:81], v[98:99], v[104:105]
	v_cvt_pk_bf16_f32 v80, v84, v85
	v_cvt_pk_bf16_f32 v81, v86, v87
	v_cvt_pk_bf16_f32 v82, v82, v83
	v_cvt_pk_bf16_f32 v83, v88, v89
	global_store_dwordx4 v[96:97], v[80:83], off
	s_nop 1
	v_or_b32_e32 v80, 48, v140
	v_ashrrev_i32_e32 v81, 31, v80
	v_lshlrev_b64 v[80:81], 10, v[80:81]
	v_lshl_add_u64 v[80:81], v[80:81], 0, v[138:139]
	v_lshlrev_b64 v[80:81], 1, v[80:81]
	v_lshl_add_u64 v[82:83], s[8:9], 0, v[80:81]
	v_lshl_add_u64 v[94:95], s[10:11], 0, v[80:81]
	v_or_b32_e32 v80, 0x100, v80
	s_waitcnt vmcnt(16)
	v_mov_b64_e32 v[82:83], v[166:167]
	v_mov_b64_e32 v[84:85], v[168:169]
	v_lshlrev_b32_e32 v86, 16, v82
	v_and_b32_e32 v87, 0xffff0000, v82
	v_lshlrev_b32_e32 v88, 16, v83
	v_and_b32_e32 v89, 0xffff0000, v83
	v_lshlrev_b32_e32 v90, 16, v84
	v_and_b32_e32 v91, 0xffff0000, v84
	v_lshlrev_b32_e32 v92, 16, v85
	v_and_b32_e32 v93, 0xffff0000, v85
	s_waitcnt vmcnt(15)
; __device__ __forceinline__ u32x4 pack8(const f32x4 a, const f32x4 b) { u32x4 w; w.x = cvt_pk_bf16(a[0], a[1]); w.y = cvt_pk_bf16(a[2], a[3]); w.z = cvt_pk_bf16(b[0], b[1]); w.w = cvt_pk_bf16(b[2], b[3]); return w; }
; #define G opaque_s(G0)
;     __device__ __forceinline__ void operator()(const f32x4 (&acc)[2][2][4][2], const Unit& u, int wr, int wc, int fr, int fq) const {
;         const int row0 = u.pm * BM + wr * 64 + fr, col0 = u.pn * BM + wc * 32 + 8 * fq;
; #pragma unroll
;         for (int ai = 0; ai < 2; ++ai)
; #pragma unroll
;             for (int m = 0; m < 4; ++m) { if ((m & 1) == 0) asm volatile("" ::: "memory"); const int row = row0 + ai * HALF + m * 16;
; #pragma unroll
;                 for (int bj = 0; bj < 2; ++bj) { const size_t off = (size_t)row * 1024 + col0 + bj * HALF;
;                     f32x4 g0, g1; unpack8(*(const u32x4*)(G + off), g0, g1);
;                     f32x4 o0 = acc[ai][bj][m][0] * g0, o1 = acc[ai][bj][m][1] * g1;
;                     if (!first) { f32x4 p0, p1; unpack8(*(const u32x4*)(Mg + off), p0, p1); o0 = o0 + p0; o1 = o1 + p1; }
;                     *(u32x4*)(Mg + off) = pack8(o0, o1); } }
	v_mov_b64_e32 v[82:83], v[170:171]
	v_mov_b64_e32 v[84:85], v[172:173]
	v_lshlrev_b32_e32 v96, 16, v82
	v_and_b32_e32 v97, 0xffff0000, v82
	v_lshlrev_b32_e32 v82, 16, v83
	v_and_b32_e32 v83, 0xffff0000, v83
	v_lshlrev_b32_e32 v98, 16, v84
	v_and_b32_e32 v99, 0xffff0000, v84
	v_lshlrev_b32_e32 v84, 16, v85
	v_and_b32_e32 v85, 0xffff0000, v85
	v_pk_fma_f32 v[78:79], v[78:79], v[88:89], v[82:83]
	v_pk_fma_f32 v[76:77], v[76:77], v[86:87], v[96:97]
	v_pk_fma_f32 v[82:83], v[74:75], v[92:93], v[84:85]
	v_pk_fma_f32 v[74:75], v[72:73], v[90:91], v[98:99]
	v_cvt_pk_bf16_f32 v72, v76, v77
	v_cvt_pk_bf16_f32 v73, v78, v79
	v_cvt_pk_bf16_f32 v74, v74, v75
	v_cvt_pk_bf16_f32 v75, v82, v83
	global_store_dwordx4 v[94:95], v[72:75], off
	s_nop 1
	v_lshl_add_u64 v[72:73], s[8:9], 0, v[80:81]
	v_lshl_add_u64 v[80:81], s[10:11], 0, v[80:81]
	s_waitcnt vmcnt(15)
	v_mov_b64_e32 v[72:73], v[174:175]
	v_mov_b64_e32 v[74:75], v[176:177]
	v_lshlrev_b32_e32 v76, 16, v72
	v_and_b32_e32 v77, 0xffff0000, v72
	v_lshlrev_b32_e32 v78, 16, v73
	v_and_b32_e32 v79, 0xffff0000, v73
	v_lshlrev_b32_e32 v82, 16, v74
	v_and_b32_e32 v83, 0xffff0000, v74
	v_lshlrev_b32_e32 v84, 16, v75
	v_and_b32_e32 v85, 0xffff0000, v75
	s_waitcnt vmcnt(14)
	v_mov_b64_e32 v[72:73], v[178:179]
	v_mov_b64_e32 v[74:75], v[180:181]
	s_add_u32 s60, s8, 0x50000
	s_addc_u32 s61, s9, 0
	s_add_u32 s62, s10, 0x50000
	s_addc_u32 s63, s11, 0
	global_load_dwordx4 v[166:169], v136, s[60:61]
	global_load_dwordx4 v[170:173], v136, s[62:63]
	global_load_dwordx4 v[174:177], v136, s[60:61] offset:256
	global_load_dwordx4 v[178:181], v136, s[62:63] offset:256
	v_lshlrev_b32_e32 v86, 16, v72
	v_and_b32_e32 v87, 0xffff0000, v72
	v_lshlrev_b32_e32 v72, 16, v73
	v_and_b32_e32 v73, 0xffff0000, v73
	v_lshlrev_b32_e32 v88, 16, v74
	v_and_b32_e32 v89, 0xffff0000, v74
	v_lshlrev_b32_e32 v74, 16, v75
	v_and_b32_e32 v75, 0xffff0000, v75
	v_pk_fma_f32 v[70:71], v[70:71], v[78:79], v[72:73]
	v_pk_fma_f32 v[68:69], v[68:69], v[76:77], v[86:87]
	v_pk_fma_f32 v[72:73], v[66:67], v[84:85], v[74:75]
	v_pk_fma_f32 v[66:67], v[64:65], v[82:83], v[88:89]
	v_cvt_pk_bf16_f32 v64, v68, v69
	v_cvt_pk_bf16_f32 v65, v70, v71
	v_cvt_pk_bf16_f32 v66, v66, v67
	v_cvt_pk_bf16_f32 v67, v72, v73
	global_store_dwordx4 v[80:81], v[64:67], off
	v_lshl_add_u64 v[68:69], v[136:137], 0, s[90:91]
	s_nop 0
	v_lshl_add_u64 v[64:65], s[8:9], 0, v[68:69]
	v_lshl_add_u64 v[68:69], s[10:11], 0, v[68:69]
	s_waitcnt vmcnt(16)
	v_mov_b64_e32 v[64:65], v[182:183]
	v_mov_b64_e32 v[66:67], v[184:185]
	v_lshlrev_b32_e32 v70, 16, v64
	v_and_b32_e32 v71, 0xffff0000, v64
	v_lshlrev_b32_e32 v72, 16, v65
	v_and_b32_e32 v73, 0xffff0000, v65
	v_lshlrev_b32_e32 v74, 16, v66
	v_and_b32_e32 v75, 0xffff0000, v66
	v_lshlrev_b32_e32 v76, 16, v67
	v_and_b32_e32 v77, 0xffff0000, v67
	s_waitcnt vmcnt(15)
	v_mov_b64_e32 v[64:65], v[186:187]
	v_mov_b64_e32 v[66:67], v[188:189]
	v_lshlrev_b32_e32 v78, 16, v64
	v_and_b32_e32 v79, 0xffff0000, v64
	v_lshlrev_b32_e32 v64, 16, v65
	v_and_b32_e32 v65, 0xffff0000, v65
	v_lshlrev_b32_e32 v80, 16, v66
	v_and_b32_e32 v81, 0xffff0000, v66
	v_lshlrev_b32_e32 v66, 16, v67
	v_and_b32_e32 v67, 0xffff0000, v67
	v_pk_fma_f32 v[62:63], v[62:63], v[72:73], v[64:65]
	v_pk_fma_f32 v[60:61], v[60:61], v[70:71], v[78:79]
	v_pk_fma_f32 v[64:65], v[58:59], v[76:77], v[66:67]
	v_pk_fma_f32 v[58:59], v[56:57], v[74:75], v[80:81]
	v_cvt_pk_bf16_f32 v56, v60, v61
	v_cvt_pk_bf16_f32 v57, v62, v63
	v_cvt_pk_bf16_f32 v58, v58, v59
	v_cvt_pk_bf16_f32 v59, v64, v65
	v_lshl_add_u64 v[60:61], v[136:137], 0, s[0:1]
	global_store_dwordx4 v[68:69], v[56:59], off
	s_mov_b64 s[0:1], 0x48000
	s_nop 0
	v_lshl_add_u64 v[56:57], s[8:9], 0, v[60:61]
	v_lshl_add_u64 v[60:61], s[10:11], 0, v[60:61]
	s_waitcnt vmcnt(15)
	v_mov_b64_e32 v[56:57], v[190:191]
	v_mov_b64_e32 v[58:59], v[192:193]
	v_lshlrev_b32_e32 v62, 16, v56
	v_and_b32_e32 v63, 0xffff0000, v56
	v_lshlrev_b32_e32 v64, 16, v57
	v_and_b32_e32 v65, 0xffff0000, v57
	v_lshlrev_b32_e32 v66, 16, v58
	v_and_b32_e32 v67, 0xffff0000, v58
	v_lshlrev_b32_e32 v68, 16, v59
	v_and_b32_e32 v69, 0xffff0000, v59
	s_waitcnt vmcnt(14)
	v_mov_b64_e32 v[56:57], v[194:195]
	v_mov_b64_e32 v[58:59], v[196:197]
	s_add_u32 s60, s8, 0x58000
	s_addc_u32 s61, s9, 0
	s_add_u32 s62, s10, 0x58000
	s_addc_u32 s63, s11, 0
	global_load_dwordx4 v[182:185], v136, s[60:61]
	global_load_dwordx4 v[186:189], v136, s[62:63]
	global_load_dwordx4 v[190:193], v136, s[60:61] offset:256
	global_load_dwordx4 v[194:197], v136, s[62:63] offset:256
	v_lshlrev_b32_e32 v70, 16, v56
	v_and_b32_e32 v71, 0xffff0000, v56
	v_lshlrev_b32_e32 v56, 16, v57
	v_and_b32_e32 v57, 0xffff0000, v57
	v_lshlrev_b32_e32 v72, 16, v58
	v_and_b32_e32 v73, 0xffff0000, v58
	v_lshlrev_b32_e32 v58, 16, v59
	v_and_b32_e32 v59, 0xffff0000, v59
	v_pk_fma_f32 v[54:55], v[54:55], v[64:65], v[56:57]
	v_pk_fma_f32 v[52:53], v[52:53], v[62:63], v[70:71]
	v_pk_fma_f32 v[56:57], v[50:51], v[68:69], v[58:59]
	v_pk_fma_f32 v[50:51], v[48:49], v[66:67], v[72:73]
	v_cvt_pk_bf16_f32 v48, v52, v53
	v_cvt_pk_bf16_f32 v49, v54, v55
	v_cvt_pk_bf16_f32 v50, v50, v51
	v_cvt_pk_bf16_f32 v51, v56, v57
	v_lshl_add_u64 v[52:53], v[136:137], 0, s[0:1]
	global_store_dwordx4 v[60:61], v[48:51], off
	s_mov_b64 s[0:1], 0x48100
	s_nop 0
	v_lshl_add_u64 v[48:49], s[8:9], 0, v[52:53]
	v_lshl_add_u64 v[52:53], s[10:11], 0, v[52:53]
	s_waitcnt vmcnt(16)
	v_mov_b64_e32 v[48:49], v[198:199]
	v_mov_b64_e32 v[50:51], v[200:201]
	v_lshlrev_b32_e32 v54, 16, v48
	v_and_b32_e32 v55, 0xffff0000, v48
	v_lshlrev_b32_e32 v56, 16, v49
	v_and_b32_e32 v57, 0xffff0000, v49
	v_lshlrev_b32_e32 v58, 16, v50
	v_and_b32_e32 v59, 0xffff0000, v50
	v_lshlrev_b32_e32 v60, 16, v51
	v_and_b32_e32 v61, 0xffff0000, v51
	s_waitcnt vmcnt(15)
; __device__ __forceinline__ u32x4 pack8(const f32x4 a, const f32x4 b) { u32x4 w; w.x = cvt_pk_bf16(a[0], a[1]); w.y = cvt_pk_bf16(a[2], a[3]); w.z = cvt_pk_bf16(b[0], b[1]); w.w = cvt_pk_bf16(b[2], b[3]); return w; }
; #define G opaque_s(G0)
;     __device__ __forceinline__ void operator()(const f32x4 (&acc)[2][2][4][2], const Unit& u, int wr, int wc, int fr, int fq) const {
;         const int row0 = u.pm * BM + wr * 64 + fr, col0 = u.pn * BM + wc * 32 + 8 * fq;
; #pragma unroll
;         for (int ai = 0; ai < 2; ++ai)
; #pragma unroll
;             for (int m = 0; m < 4; ++m) { if ((m & 1) == 0) asm volatile("" ::: "memory"); const int row = row0 + ai * HALF + m * 16;
; #pragma unroll
;                 for (int bj = 0; bj < 2; ++bj) { const size_t off = (size_t)row * 1024 + col0 + bj * HALF;
;                     f32x4 g0, g1; unpack8(*(const u32x4*)(G + off), g0, g1);
;                     f32x4 o0 = acc[ai][bj][m][0] * g0, o1 = acc[ai][bj][m][1] * g1;
;                     if (!first) { f32x4 p0, p1; unpack8(*(const u32x4*)(Mg + off), p0, p1); o0 = o0 + p0; o1 = o1 + p1; }
;                     *(u32x4*)(Mg + off) = pack8(o0, o1); } }
	v_mov_b64_e32 v[48:49], v[202:203]
	v_mov_b64_e32 v[50:51], v[204:205]
	v_lshlrev_b32_e32 v62, 16, v48
	v_and_b32_e32 v63, 0xffff0000, v48
	v_lshlrev_b32_e32 v48, 16, v49
	v_and_b32_e32 v49, 0xffff0000, v49
	v_lshlrev_b32_e32 v64, 16, v50
	v_and_b32_e32 v65, 0xffff0000, v50
	v_lshlrev_b32_e32 v50, 16, v51
	v_and_b32_e32 v51, 0xffff0000, v51
	v_pk_fma_f32 v[46:47], v[46:47], v[56:57], v[48:49]
	v_pk_fma_f32 v[44:45], v[44:45], v[54:55], v[62:63]
	v_pk_fma_f32 v[48:49], v[42:43], v[60:61], v[50:51]
	v_pk_fma_f32 v[42:43], v[40:41], v[58:59], v[64:65]
	v_cvt_pk_bf16_f32 v40, v44, v45
	v_cvt_pk_bf16_f32 v41, v46, v47
	v_cvt_pk_bf16_f32 v42, v42, v43
	v_cvt_pk_bf16_f32 v43, v48, v49
	v_lshl_add_u64 v[44:45], v[136:137], 0, s[0:1]
	global_store_dwordx4 v[52:53], v[40:43], off
	s_mov_b64 s[0:1], 0x50000
	s_nop 0
	v_lshl_add_u64 v[40:41], s[8:9], 0, v[44:45]
	v_lshl_add_u64 v[44:45], s[10:11], 0, v[44:45]
	s_waitcnt vmcnt(15)
	v_mov_b64_e32 v[40:41], v[206:207]
	v_mov_b64_e32 v[42:43], v[208:209]
	v_lshlrev_b32_e32 v46, 16, v40
	v_and_b32_e32 v47, 0xffff0000, v40
	v_lshlrev_b32_e32 v48, 16, v41
	v_and_b32_e32 v49, 0xffff0000, v41
	v_lshlrev_b32_e32 v50, 16, v42
	v_and_b32_e32 v51, 0xffff0000, v42
	v_lshlrev_b32_e32 v52, 16, v43
	v_and_b32_e32 v53, 0xffff0000, v43
	s_waitcnt vmcnt(14)
	v_mov_b64_e32 v[40:41], v[210:211]
	v_mov_b64_e32 v[42:43], v[212:213]
	v_lshlrev_b32_e32 v54, 16, v40
	v_and_b32_e32 v55, 0xffff0000, v40
	v_lshlrev_b32_e32 v40, 16, v41
	v_and_b32_e32 v41, 0xffff0000, v41
	v_lshlrev_b32_e32 v56, 16, v42
	v_and_b32_e32 v57, 0xffff0000, v42
	v_lshlrev_b32_e32 v42, 16, v43
	v_and_b32_e32 v43, 0xffff0000, v43
	v_pk_fma_f32 v[38:39], v[38:39], v[48:49], v[40:41]
	v_pk_fma_f32 v[36:37], v[36:37], v[46:47], v[54:55]
	v_pk_fma_f32 v[40:41], v[34:35], v[52:53], v[42:43]
	v_pk_fma_f32 v[34:35], v[32:33], v[50:51], v[56:57]
	v_cvt_pk_bf16_f32 v32, v36, v37
	v_cvt_pk_bf16_f32 v33, v38, v39
	v_cvt_pk_bf16_f32 v34, v34, v35
	v_cvt_pk_bf16_f32 v35, v40, v41
	global_store_dwordx4 v[44:45], v[32:35], off
	v_lshl_add_u64 v[36:37], v[136:137], 0, s[0:1]
	s_mov_b64 s[0:1], 0x50100
	v_lshl_add_u64 v[32:33], s[8:9], 0, v[36:37]
	v_lshl_add_u64 v[36:37], s[10:11], 0, v[36:37]
	s_waitcnt vmcnt(12)
	v_mov_b64_e32 v[32:33], v[166:167]
	v_mov_b64_e32 v[34:35], v[168:169]
	v_lshlrev_b32_e32 v38, 16, v32
	v_and_b32_e32 v39, 0xffff0000, v32
	v_lshlrev_b32_e32 v40, 16, v33
	v_and_b32_e32 v41, 0xffff0000, v33
	v_lshlrev_b32_e32 v42, 16, v34
	v_and_b32_e32 v43, 0xffff0000, v34
	v_lshlrev_b32_e32 v44, 16, v35
	v_and_b32_e32 v45, 0xffff0000, v35
	s_waitcnt vmcnt(11)
	v_mov_b64_e32 v[32:33], v[170:171]
	v_mov_b64_e32 v[34:35], v[172:173]
	v_lshlrev_b32_e32 v46, 16, v32
	v_and_b32_e32 v47, 0xffff0000, v32
	v_lshlrev_b32_e32 v32, 16, v33
	v_and_b32_e32 v33, 0xffff0000, v33
	v_lshlrev_b32_e32 v48, 16, v34
	v_and_b32_e32 v49, 0xffff0000, v34
	v_lshlrev_b32_e32 v34, 16, v35
	v_and_b32_e32 v35, 0xffff0000, v35
	v_pk_fma_f32 v[30:31], v[30:31], v[40:41], v[32:33]
	v_pk_fma_f32 v[28:29], v[28:29], v[38:39], v[46:47]
	v_pk_fma_f32 v[32:33], v[26:27], v[44:45], v[34:35]
	v_pk_fma_f32 v[26:27], v[24:25], v[42:43], v[48:49]
	v_cvt_pk_bf16_f32 v24, v28, v29
	v_cvt_pk_bf16_f32 v25, v30, v31
	v_cvt_pk_bf16_f32 v26, v26, v27
	v_cvt_pk_bf16_f32 v27, v32, v33
	v_lshl_add_u64 v[28:29], v[136:137], 0, s[0:1]
	global_store_dwordx4 v[36:37], v[24:27], off
	s_mov_b64 s[0:1], 0x58100
	s_nop 0
	v_lshl_add_u64 v[24:25], s[8:9], 0, v[28:29]
	v_lshl_add_u64 v[28:29], s[10:11], 0, v[28:29]
	s_waitcnt vmcnt(11)
; __device__ __forceinline__ u32x4 pack8(const f32x4 a, const f32x4 b) { u32x4 w; w.x = cvt_pk_bf16(a[0], a[1]); w.y = cvt_pk_bf16(a[2], a[3]); w.z = cvt_pk_bf16(b[0], b[1]); w.w = cvt_pk_bf16(b[2], b[3]); return w; }
; #define G opaque_s(G0)
;     __device__ __forceinline__ void operator()(const f32x4 (&acc)[2][2][4][2], const Unit& u, int wr, int wc, int fr, int fq) const {
;         const int row0 = u.pm * BM + wr * 64 + fr, col0 = u.pn * BM + wc * 32 + 8 * fq;
; #pragma unroll
;         for (int ai = 0; ai < 2; ++ai)
; #pragma unroll
;             for (int m = 0; m < 4; ++m) { if ((m & 1) == 0) asm volatile("" ::: "memory"); const int row = row0 + ai * HALF + m * 16;
; #pragma unroll
;                 for (int bj = 0; bj < 2; ++bj) { const size_t off = (size_t)row * 1024 + col0 + bj * HALF;
;                     f32x4 g0, g1; unpack8(*(const u32x4*)(G + off), g0, g1);
;                     f32x4 o0 = acc[ai][bj][m][0] * g0, o1 = acc[ai][bj][m][1] * g1;
;                     if (!first) { f32x4 p0, p1; unpack8(*(const u32x4*)(Mg + off), p0, p1); o0 = o0 + p0; o1 = o1 + p1; }
;                     *(u32x4*)(Mg + off) = pack8(o0, o1); } }
	v_mov_b64_e32 v[24:25], v[174:175]
	v_mov_b64_e32 v[26:27], v[176:177]
	v_lshlrev_b32_e32 v30, 16, v24
	v_and_b32_e32 v31, 0xffff0000, v24
	v_lshlrev_b32_e32 v32, 16, v25
	v_and_b32_e32 v33, 0xffff0000, v25
	v_lshlrev_b32_e32 v34, 16, v26
	v_and_b32_e32 v35, 0xffff0000, v26
	v_lshlrev_b32_e32 v36, 16, v27
	v_and_b32_e32 v37, 0xffff0000, v27
	s_waitcnt vmcnt(10)
	v_mov_b64_e32 v[24:25], v[178:179]
	v_mov_b64_e32 v[26:27], v[180:181]
	v_lshlrev_b32_e32 v38, 16, v24
	v_and_b32_e32 v39, 0xffff0000, v24
	v_lshlrev_b32_e32 v24, 16, v25
	v_and_b32_e32 v25, 0xffff0000, v25
	v_lshlrev_b32_e32 v40, 16, v26
	v_and_b32_e32 v41, 0xffff0000, v26
	v_lshlrev_b32_e32 v26, 16, v27
	v_and_b32_e32 v27, 0xffff0000, v27
	v_pk_fma_f32 v[22:23], v[22:23], v[32:33], v[24:25]
	v_pk_fma_f32 v[20:21], v[20:21], v[30:31], v[38:39]
	v_pk_fma_f32 v[24:25], v[18:19], v[36:37], v[26:27]
	v_pk_fma_f32 v[18:19], v[16:17], v[34:35], v[40:41]
	v_cvt_pk_bf16_f32 v16, v20, v21
	v_cvt_pk_bf16_f32 v17, v22, v23
	v_cvt_pk_bf16_f32 v18, v18, v19
	v_cvt_pk_bf16_f32 v19, v24, v25
	v_lshl_add_u64 v[20:21], v[136:137], 0, s[78:79]
	global_store_dwordx4 v[28:29], v[16:19], off
	s_nop 1
	v_lshl_add_u64 v[16:17], s[8:9], 0, v[20:21]
	v_lshl_add_u64 v[20:21], s[10:11], 0, v[20:21]
	s_waitcnt vmcnt(8)
	v_mov_b64_e32 v[16:17], v[182:183]
	v_mov_b64_e32 v[18:19], v[184:185]
	v_lshlrev_b32_e32 v22, 16, v16
	v_and_b32_e32 v23, 0xffff0000, v16
	v_lshlrev_b32_e32 v24, 16, v17
	v_and_b32_e32 v25, 0xffff0000, v17
	v_lshlrev_b32_e32 v26, 16, v18
	v_and_b32_e32 v27, 0xffff0000, v18
	v_lshlrev_b32_e32 v28, 16, v19
	v_and_b32_e32 v29, 0xffff0000, v19
	s_waitcnt vmcnt(7)
	v_mov_b64_e32 v[16:17], v[186:187]
	v_mov_b64_e32 v[18:19], v[188:189]
	v_lshlrev_b32_e32 v30, 16, v16
	v_and_b32_e32 v31, 0xffff0000, v16
	v_lshlrev_b32_e32 v16, 16, v17
	v_and_b32_e32 v17, 0xffff0000, v17
	v_lshlrev_b32_e32 v32, 16, v18
	v_and_b32_e32 v33, 0xffff0000, v18
	v_lshlrev_b32_e32 v18, 16, v19
	v_and_b32_e32 v19, 0xffff0000, v19
	v_pk_fma_f32 v[14:15], v[14:15], v[24:25], v[16:17]
	v_pk_fma_f32 v[12:13], v[12:13], v[22:23], v[30:31]
	v_pk_fma_f32 v[16:17], v[10:11], v[28:29], v[18:19]
	v_pk_fma_f32 v[10:11], v[8:9], v[26:27], v[32:33]
	v_cvt_pk_bf16_f32 v8, v12, v13
	v_cvt_pk_bf16_f32 v9, v14, v15
	v_cvt_pk_bf16_f32 v10, v10, v11
	v_cvt_pk_bf16_f32 v11, v16, v17
	v_lshl_add_u64 v[12:13], v[136:137], 0, s[0:1]
	global_store_dwordx4 v[20:21], v[8:11], off
	s_mov_b64 s[0:1], -1
	s_nop 0
	v_lshl_add_u64 v[8:9], s[8:9], 0, v[12:13]
	v_lshl_add_u64 v[12:13], s[10:11], 0, v[12:13]
	s_waitcnt vmcnt(7)
	v_mov_b64_e32 v[8:9], v[190:191]
	v_mov_b64_e32 v[10:11], v[192:193]
	v_lshlrev_b32_e32 v14, 16, v8
	v_and_b32_e32 v15, 0xffff0000, v8
	v_lshlrev_b32_e32 v16, 16, v9
	v_and_b32_e32 v17, 0xffff0000, v9
	v_lshlrev_b32_e32 v18, 16, v10
	v_and_b32_e32 v19, 0xffff0000, v10
	v_lshlrev_b32_e32 v20, 16, v11
	v_and_b32_e32 v21, 0xffff0000, v11
	s_waitcnt vmcnt(6)
	v_mov_b64_e32 v[8:9], v[194:195]
	v_mov_b64_e32 v[10:11], v[196:197]
	v_lshlrev_b32_e32 v22, 16, v8
	v_and_b32_e32 v23, 0xffff0000, v8
	v_lshlrev_b32_e32 v8, 16, v9
	v_and_b32_e32 v9, 0xffff0000, v9
	v_lshlrev_b32_e32 v24, 16, v10
	v_and_b32_e32 v25, 0xffff0000, v10
	v_lshlrev_b32_e32 v10, 16, v11
	v_and_b32_e32 v11, 0xffff0000, v11
	v_pk_fma_f32 v[6:7], v[6:7], v[16:17], v[8:9]
	v_pk_fma_f32 v[4:5], v[4:5], v[14:15], v[22:23]
	v_pk_fma_f32 v[8:9], v[2:3], v[20:21], v[10:11]
	v_pk_fma_f32 v[2:3], v[0:1], v[18:19], v[24:25]
	v_cvt_pk_bf16_f32 v0, v4, v5
	v_cvt_pk_bf16_f32 v1, v6, v7
	v_cvt_pk_bf16_f32 v2, v2, v3
	v_cvt_pk_bf16_f32 v3, v8, v9
	global_store_dwordx4 v[12:13], v[0:3], off
	s_cbranch_vccnz .LBB0_1549
	s_andn2_b64 vcc, exec, s[6:7]
	s_cbranch_vccnz .LBB0_1548
	s_barrier
	s_branch .LBB0_1548
